# nt on G3 pass-2 r-fragment loads (last reader of layer 1's r projection)
# baseline (speedup 1.0000x reference)
.LBB0_1377:
	s_or_b64 exec, exec, s[6:7]
	s_ashr_i32 s0, s24, 2
	s_ashr_i32 s1, s0, 31
	s_lshl_b64 s[0:1], s[0:1], 6
	s_lshl_b32 s6, s23, 5
	s_or_b32 s0, s0, s6
	v_lshlrev_b32_e32 v12, 4, v205
	v_or_b32_e32 v22, s0, v204
	v_mov_b32_e32 v23, s1
	v_readlane_b32 s68, v251, 9
	v_lshlrev_b64 v[26:27], 11, v[22:23]
	v_lshl_or_b32 v28, s44, 1, v12
	v_lshlrev_b32_e32 v10, 5, v205
	v_readlane_b32 s76, v251, 17
	v_readlane_b32 s77, v251, 18
	v_or_b32_e32 v26, v26, v28
	s_nop 3
	global_load_dwordx4 v[2:5], v10, s[76:77] offset:16
	global_load_dwordx4 v[6:9], v10, s[76:77]
	s_waitcnt lgkmcnt(0)
	v_lshl_add_u64 v[10:11], s[60:61], 0, v[26:27]
	global_load_dwordx4 v[18:21], v[10:11], off nt
	v_or_b32_e32 v128, 2, v22
	v_mov_b32_e32 v129, v23
	v_lshlrev_b64 v[130:131], 11, v[128:129]
	v_or_b32_e32 v130, v130, v28
	v_lshl_add_u64 v[128:129], s[60:61], 0, v[130:131]
	global_load_dwordx4 v[64:67], v[128:129], off nt
	v_or_b32_e32 v128, 4, v22
	v_mov_b32_e32 v129, v23
	v_lshlrev_b64 v[130:131], 11, v[128:129]
	v_or_b32_e32 v130, v130, v28
	v_lshl_add_u64 v[128:129], s[60:61], 0, v[130:131]
	global_load_dwordx4 v[68:71], v[128:129], off nt
	v_or_b32_e32 v128, 6, v22
	v_mov_b32_e32 v129, v23
	v_lshlrev_b64 v[130:131], 11, v[128:129]
	v_or_b32_e32 v130, v130, v28
	v_lshl_add_u64 v[128:129], s[60:61], 0, v[130:131]
	global_load_dwordx4 v[72:75], v[128:129], off nt
	v_or_b32_e32 v128, 8, v22
	v_mov_b32_e32 v129, v23
	v_lshlrev_b64 v[130:131], 11, v[128:129]
	v_or_b32_e32 v130, v130, v28
	v_lshl_add_u64 v[128:129], s[60:61], 0, v[130:131]
	global_load_dwordx4 v[76:79], v[128:129], off nt
	v_or_b32_e32 v128, 10, v22
	v_mov_b32_e32 v129, v23
	v_lshlrev_b64 v[130:131], 11, v[128:129]
	v_or_b32_e32 v130, v130, v28
	v_lshl_add_u64 v[128:129], s[60:61], 0, v[130:131]
	global_load_dwordx4 v[80:83], v[128:129], off nt
	v_or_b32_e32 v128, 12, v22
	v_mov_b32_e32 v129, v23
	v_lshlrev_b64 v[130:131], 11, v[128:129]
	v_or_b32_e32 v130, v130, v28
	v_lshl_add_u64 v[128:129], s[60:61], 0, v[130:131]
	global_load_dwordx4 v[84:87], v[128:129], off nt
	v_or_b32_e32 v128, 14, v22
	v_mov_b32_e32 v129, v23
	v_lshlrev_b64 v[130:131], 11, v[128:129]
	v_or_b32_e32 v130, v130, v28
	v_lshl_add_u64 v[128:129], s[60:61], 0, v[130:131]
	global_load_dwordx4 v[88:91], v[128:129], off nt
	v_or_b32_e32 v128, 16, v22
	v_mov_b32_e32 v129, v23
	v_lshlrev_b64 v[130:131], 11, v[128:129]
	v_or_b32_e32 v130, v130, v28
	v_lshl_add_u64 v[128:129], s[60:61], 0, v[130:131]
	global_load_dwordx4 v[92:95], v[128:129], off nt
	v_or_b32_e32 v128, 18, v22
	v_mov_b32_e32 v129, v23
	v_lshlrev_b64 v[130:131], 11, v[128:129]
	v_or_b32_e32 v130, v130, v28
	v_lshl_add_u64 v[128:129], s[60:61], 0, v[130:131]
	global_load_dwordx4 v[96:99], v[128:129], off nt
	v_or_b32_e32 v128, 20, v22
	v_mov_b32_e32 v129, v23
	v_lshlrev_b64 v[130:131], 11, v[128:129]
	v_or_b32_e32 v130, v130, v28
	v_lshl_add_u64 v[128:129], s[60:61], 0, v[130:131]
	global_load_dwordx4 v[100:103], v[128:129], off nt
	v_or_b32_e32 v128, 22, v22
	v_mov_b32_e32 v129, v23
	v_lshlrev_b64 v[130:131], 11, v[128:129]
	v_or_b32_e32 v130, v130, v28
	v_lshl_add_u64 v[128:129], s[60:61], 0, v[130:131]
	global_load_dwordx4 v[104:107], v[128:129], off nt
	v_or_b32_e32 v128, 24, v22
	v_mov_b32_e32 v129, v23
	v_lshlrev_b64 v[130:131], 11, v[128:129]
	v_or_b32_e32 v130, v130, v28
	v_lshl_add_u64 v[128:129], s[60:61], 0, v[130:131]
	global_load_dwordx4 v[108:111], v[128:129], off nt
	v_or_b32_e32 v128, 26, v22
	v_mov_b32_e32 v129, v23
	v_lshlrev_b64 v[130:131], 11, v[128:129]
	v_or_b32_e32 v130, v130, v28
	v_lshl_add_u64 v[128:129], s[60:61], 0, v[130:131]
	global_load_dwordx4 v[112:115], v[128:129], off nt
	v_or_b32_e32 v128, 28, v22
	v_mov_b32_e32 v129, v23
	v_lshlrev_b64 v[130:131], 11, v[128:129]
	v_or_b32_e32 v130, v130, v28
	v_lshl_add_u64 v[128:129], s[60:61], 0, v[130:131]
	global_load_dwordx4 v[116:119], v[128:129], off nt
	v_or_b32_e32 v128, 30, v22
	v_mov_b32_e32 v129, v23
	v_lshlrev_b64 v[130:131], 11, v[128:129]
	v_or_b32_e32 v130, v130, v28
	v_lshl_add_u64 v[128:129], s[60:61], 0, v[130:131]
	global_load_dwordx4 v[120:123], v[128:129], off nt
	s_mov_b64 s[8:9], s[76:77]
	v_mul_u32_u24_e32 v10, 0x210, v204
	v_add3_u32 v29, s22, v12, v10
	ds_read_b128 v[14:17], v29
	v_lshl_add_u32 v10, v204, 2, s22
	v_add_u32_e32 v30, 0x4000, v10
	ds_read2_b32 v[24:25], v30 offset0:128 offset1:130
	ds_read_b128 v[10:13], v29 offset:1056
	v_readlane_b32 s69, v251, 10
	s_waitcnt lgkmcnt(2)
	v_lshlrev_b32_e32 v32, 16, v14
	v_and_b32_e32 v33, 0xffff0000, v14
	s_waitcnt lgkmcnt(1)
	v_pk_mul_f32 v[32:33], v[24:25], v[32:33] op_sel_hi:[0,1]
	v_lshlrev_b32_e32 v14, 16, v15
	v_and_b32_e32 v15, 0xffff0000, v15
	v_lshlrev_b32_e32 v34, 16, v16
	v_pk_mul_f32 v[14:15], v[24:25], v[14:15] op_sel_hi:[0,1]
	v_readlane_b32 s70, v251, 11
	v_readlane_b32 s71, v251, 12
	v_readlane_b32 s72, v251, 13
	v_readlane_b32 s73, v251, 14
	v_readlane_b32 s74, v251, 15
	v_readlane_b32 s75, v251, 16
	v_readlane_b32 s78, v251, 19
	v_readlane_b32 s79, v251, 20
	v_readlane_b32 s80, v251, 21
	v_readlane_b32 s81, v251, 22
	v_readlane_b32 s82, v251, 23
	v_readlane_b32 s83, v251, 24
	s_waitcnt vmcnt(1)
	v_pk_mul_f32 v[32:33], v[6:7], v[32:33]
	v_pk_mul_f32 v[14:15], v[8:9], v[14:15]
	s_waitcnt vmcnt(0)
	v_lshlrev_b32_e32 v31, 16, v18
	v_and_b32_e32 v35, 0xffff0000, v18
	v_lshlrev_b32_e32 v40, 16, v19
	v_and_b32_e32 v41, 0xffff0000, v19
	v_mul_f32_e32 v18, 0xbfb8aa3b, v31
	v_mul_f32_e32 v19, 0xbfb8aa3b, v35
	v_exp_f32_e32 v18, v18
	v_exp_f32_e32 v19, v19
	v_mul_f32_e32 v36, 0xbfb8aa3b, v40
	v_mul_f32_e32 v37, 0xbfb8aa3b, v41
	v_exp_f32_e32 v36, v36
	v_exp_f32_e32 v37, v37
	v_pk_add_f32 v[18:19], v[18:19], 1.0 op_sel_hi:[1,0]
	v_lshlrev_b32_e32 v42, 16, v20
	v_div_scale_f32 v43, s[0:1], v19, v19, v35
	v_pk_add_f32 v[36:37], v[36:37], 1.0 op_sel_hi:[1,0]
	v_div_scale_f32 v45, s[0:1], v18, v18, v31
	v_rcp_f32_e32 v51, v43
	v_div_scale_f32 v47, s[6:7], v37, v37, v41
	v_rcp_f32_e32 v52, v45
	v_div_scale_f32 v49, s[8:9], v36, v36, v40
	v_rcp_f32_e32 v53, v47
	v_rcp_f32_e32 v54, v49
	v_fma_f32 v55, -v43, v51, 1.0
	v_div_scale_f32 v44, vcc, v35, v19, v35
	v_fma_f32 v56, -v45, v52, 1.0
	v_fmac_f32_e32 v51, v55, v51
	v_div_scale_f32 v46, s[0:1], v31, v18, v31
	v_fma_f32 v57, -v47, v53, 1.0
	v_fmac_f32_e32 v52, v56, v52
	v_mul_f32_e32 v55, v44, v51
	v_and_b32_e32 v20, 0xffff0000, v20
	v_div_scale_f32 v48, s[6:7], v41, v37, v41
	v_fma_f32 v58, -v49, v54, 1.0
	v_fmac_f32_e32 v53, v57, v53
	v_mul_f32_e32 v56, v46, v52
	v_fma_f32 v59, -v43, v55, v44
	v_mul_f32_e32 v38, 0xbfb8aa3b, v42
	v_mul_f32_e32 v39, 0xbfb8aa3b, v20
	v_div_scale_f32 v50, s[8:9], v40, v36, v40
	v_fmac_f32_e32 v54, v58, v54
	v_mul_f32_e32 v57, v48, v53
	v_fma_f32 v60, -v45, v56, v46
	v_fmac_f32_e32 v55, v59, v51
	v_exp_f32_e32 v38, v38
	v_exp_f32_e32 v39, v39
	v_mul_f32_e32 v58, v50, v54
	v_fma_f32 v61, -v47, v57, v48
	v_fmac_f32_e32 v56, v60, v52
	v_fma_f32 v43, -v43, v55, v44
	v_fma_f32 v62, -v49, v58, v50
	v_fmac_f32_e32 v57, v61, v53
	v_fma_f32 v44, -v45, v56, v46
	v_div_fmas_f32 v43, v43, v51, v55
	s_mov_b64 vcc, s[0:1]
	v_fmac_f32_e32 v58, v62, v54
	v_fma_f32 v45, -v47, v57, v48
	v_div_fixup_f32 v19, v43, v19, v35
	v_div_fmas_f32 v35, v44, v52, v56
	s_mov_b64 vcc, s[6:7]
	v_fma_f32 v46, -v49, v58, v50
	v_div_fixup_f32 v18, v35, v18, v31
	v_div_fmas_f32 v31, v45, v53, v57
	s_mov_b64 vcc, s[8:9]
	v_pk_add_f32 v[38:39], v[38:39], 1.0 op_sel_hi:[1,0]
	v_pk_mul_f32 v[18:19], v[32:33], v[18:19]
	v_div_fixup_f32 v33, v31, v37, v41
	v_div_fmas_f32 v31, v46, v54, v58
	v_div_fixup_f32 v32, v31, v36, v40
	v_div_scale_f32 v31, s[0:1], v39, v39, v20
	v_rcp_f32_e32 v36, v31
	v_and_b32_e32 v35, 0xffff0000, v16
	v_pk_mul_f32 v[32:33], v[14:15], v[32:33]
	v_pk_mul_f32 v[14:15], v[24:25], v[34:35] op_sel_hi:[0,1]
	v_fma_f32 v16, -v31, v36, 1.0
	v_fmac_f32_e32 v36, v16, v36
	v_div_scale_f32 v16, vcc, v20, v39, v20
	v_mul_f32_e32 v34, v16, v36
	v_fma_f32 v35, -v31, v34, v16
	v_fmac_f32_e32 v34, v35, v36
	v_fma_f32 v16, -v31, v34, v16
	v_div_scale_f32 v31, s[0:1], v38, v38, v42
	v_rcp_f32_e32 v37, v31
	v_div_fmas_f32 v16, v16, v36, v34
	v_div_fixup_f32 v35, v16, v39, v20
	v_and_b32_e32 v36, 0xffff0000, v21
	v_fma_f32 v16, -v31, v37, 1.0
	v_fmac_f32_e32 v37, v16, v37
	v_div_scale_f32 v16, vcc, v42, v38, v42
	v_mul_f32_e32 v20, v16, v37
	v_fma_f32 v34, -v31, v20, v16
	v_fmac_f32_e32 v20, v34, v37
	v_fma_f32 v16, -v31, v20, v16
	v_lshlrev_b32_e32 v31, 16, v21
	v_div_fmas_f32 v16, v16, v37, v20
	v_mul_f32_e32 v20, 0xbfb8aa3b, v31
	v_mul_f32_e32 v21, 0xbfb8aa3b, v36
	v_exp_f32_e32 v20, v20
	v_exp_f32_e32 v21, v21
	v_div_fixup_f32 v34, v16, v38, v42
	v_pk_mul_f32 v[14:15], v[2:3], v[14:15]
	v_pk_add_f32 v[20:21], v[20:21], 1.0 op_sel_hi:[1,0]
	s_nop 0
	v_div_scale_f32 v16, s[0:1], v21, v21, v36
	v_rcp_f32_e32 v37, v16
	v_pk_mul_f32 v[34:35], v[14:15], v[34:35]
	v_lshlrev_b32_e32 v14, 16, v17
	v_and_b32_e32 v15, 0xffff0000, v17
	v_fma_f32 v17, -v16, v37, 1.0
	v_fmac_f32_e32 v37, v17, v37
	v_div_scale_f32 v17, vcc, v36, v21, v36
	v_pk_mul_f32 v[14:15], v[24:25], v[14:15] op_sel_hi:[0,1]
	v_mul_f32_e32 v24, v17, v37
	v_fma_f32 v38, -v16, v24, v17
	v_fmac_f32_e32 v24, v38, v37
	v_div_scale_f32 v38, s[0:1], v20, v20, v31
	v_rcp_f32_e32 v39, v38
	v_fma_f32 v16, -v16, v24, v17
	v_div_fmas_f32 v16, v16, v37, v24
	v_div_fixup_f32 v17, v16, v21, v36
	v_fma_f32 v16, -v38, v39, 1.0
	v_fmac_f32_e32 v39, v16, v39
	v_div_scale_f32 v16, vcc, v31, v20, v31
	v_mul_f32_e32 v21, v16, v39
	v_fma_f32 v24, -v38, v21, v16
	v_fmac_f32_e32 v21, v24, v39
	v_fma_f32 v16, -v38, v21, v16
	v_div_fmas_f32 v16, v16, v39, v21
	v_pk_mul_f32 v[14:15], v[4:5], v[14:15]
	v_div_fixup_f32 v16, v16, v20, v31
	v_pk_mul_f32 v[20:21], v[14:15], v[16:17]
	v_cvt_pk_bf16_f32 v14, v18, v19
	v_cvt_pk_bf16_f32 v15, v32, v33
	v_cvt_pk_bf16_f32 v16, v34, v35
	v_cvt_pk_bf16_f32 v17, v20, v21
	v_lshl_add_u64 v[18:19], s[36:37], 0, v[26:27]
	global_store_dwordx4 v[18:19], v[14:17], off sc1
	s_waitcnt lgkmcnt(0)
	v_lshlrev_b32_e32 v26, 16, v10
	v_and_b32_e32 v27, 0xffff0000, v10
	v_or_b32_e32 v14, 2, v22
	v_mov_b32_e32 v15, v23
	v_lshlrev_b64 v[18:19], 11, v[14:15]
	v_or_b32_e32 v18, v18, v28
	v_lshl_add_u64 v[14:15], s[60:61], 0, v[18:19]
	v_mov_b32_e32 v10, v25
	v_pk_mul_f32 v[24:25], v[10:11], v[26:27] op_sel_hi:[0,1]
	v_pk_mul_f32 v[24:25], v[6:7], v[24:25]
	v_lshlrev_b32_e32 v31, 16, v64
	v_and_b32_e32 v14, 0xffff0000, v64
	v_mul_f32_e32 v20, 0xbfb8aa3b, v31
	v_mul_f32_e32 v21, 0xbfb8aa3b, v14
	v_exp_f32_e32 v20, v20
	v_exp_f32_e32 v21, v21
	s_nop 0
	v_pk_add_f32 v[20:21], v[20:21], 1.0 op_sel_hi:[1,0]
	s_nop 0
	v_div_scale_f32 v32, s[0:1], v21, v21, v14
	v_rcp_f32_e32 v33, v32
	s_nop 0
	v_fma_f32 v26, -v32, v33, 1.0
	v_fmac_f32_e32 v33, v26, v33
	v_div_scale_f32 v26, vcc, v14, v21, v14
	v_mul_f32_e32 v27, v26, v33
	v_fma_f32 v34, -v32, v27, v26
	v_fmac_f32_e32 v27, v34, v33
	v_fma_f32 v26, -v32, v27, v26
	v_div_scale_f32 v32, s[0:1], v20, v20, v31
	v_rcp_f32_e32 v34, v32
	v_div_fmas_f32 v26, v26, v33, v27
	v_div_fixup_f32 v21, v26, v21, v14
	v_fma_f32 v14, -v32, v34, 1.0
	v_fmac_f32_e32 v34, v14, v34
	v_div_scale_f32 v14, vcc, v31, v20, v31
	v_mul_f32_e32 v26, v14, v34
	v_fma_f32 v27, -v32, v26, v14
	v_fmac_f32_e32 v26, v27, v34
	v_fma_f32 v14, -v32, v26, v14
	v_lshlrev_b32_e32 v32, 16, v65
	v_and_b32_e32 v27, 0xffff0000, v65
	v_div_fmas_f32 v26, v14, v34, v26
	v_mul_f32_e32 v14, 0xbfb8aa3b, v32
	v_mul_f32_e32 v15, 0xbfb8aa3b, v27
	v_exp_f32_e32 v14, v14
	v_exp_f32_e32 v15, v15
	v_div_fixup_f32 v20, v26, v20, v31
	v_pk_mul_f32 v[20:21], v[24:25], v[20:21]
	v_lshlrev_b32_e32 v24, 16, v11
	v_pk_add_f32 v[14:15], v[14:15], 1.0 op_sel_hi:[1,0]
	v_and_b32_e32 v25, 0xffff0000, v11
	v_div_scale_f32 v26, s[0:1], v15, v15, v27
	v_rcp_f32_e32 v31, v26
	v_pk_mul_f32 v[24:25], v[10:11], v[24:25] op_sel_hi:[0,1]
	v_pk_mul_f32 v[24:25], v[8:9], v[24:25]
	v_fma_f32 v11, -v26, v31, 1.0
	v_fmac_f32_e32 v31, v11, v31
	v_div_scale_f32 v11, vcc, v27, v15, v27
	v_mul_f32_e32 v33, v11, v31
	v_fma_f32 v34, -v26, v33, v11
	v_fmac_f32_e32 v33, v34, v31
	v_fma_f32 v11, -v26, v33, v11
	v_div_scale_f32 v26, s[0:1], v14, v14, v32
	v_rcp_f32_e32 v34, v26
	v_div_fmas_f32 v11, v11, v31, v33
	v_div_fixup_f32 v15, v11, v15, v27
	v_fma_f32 v11, -v26, v34, 1.0
	v_fmac_f32_e32 v34, v11, v34
	v_div_scale_f32 v11, vcc, v32, v14, v32
	v_mul_f32_e32 v27, v11, v34
	v_fma_f32 v31, -v26, v27, v11
	v_fmac_f32_e32 v27, v31, v34
	v_fma_f32 v11, -v26, v27, v11
	v_lshlrev_b32_e32 v31, 16, v66
	v_and_b32_e32 v16, 0xffff0000, v66
	v_div_fmas_f32 v11, v11, v34, v27
	v_mul_f32_e32 v26, 0xbfb8aa3b, v31
	v_mul_f32_e32 v27, 0xbfb8aa3b, v16
	v_exp_f32_e32 v26, v26
	v_exp_f32_e32 v27, v27
	v_div_fixup_f32 v14, v11, v14, v32
	v_pk_mul_f32 v[14:15], v[24:25], v[14:15]
	v_lshlrev_b32_e32 v24, 16, v12
	v_pk_add_f32 v[26:27], v[26:27], 1.0 op_sel_hi:[1,0]
	v_and_b32_e32 v25, 0xffff0000, v12
	v_div_scale_f32 v11, s[0:1], v27, v27, v16
	v_rcp_f32_e32 v32, v11
	v_pk_mul_f32 v[24:25], v[10:11], v[24:25] op_sel_hi:[0,1]
	v_pk_mul_f32 v[24:25], v[2:3], v[24:25]
	v_fma_f32 v12, -v11, v32, 1.0
	v_fmac_f32_e32 v32, v12, v32
	v_div_scale_f32 v12, vcc, v16, v27, v16
	v_mul_f32_e32 v33, v12, v32
	v_fma_f32 v34, -v11, v33, v12
	v_fmac_f32_e32 v33, v34, v32
	v_fma_f32 v11, -v11, v33, v12
	v_div_scale_f32 v12, s[0:1], v26, v26, v31
	v_rcp_f32_e32 v34, v12
	v_div_fmas_f32 v11, v11, v32, v33
	v_div_fixup_f32 v27, v11, v27, v16
	v_and_b32_e32 v33, 0xffff0000, v67
	v_fma_f32 v11, -v12, v34, 1.0
	v_fmac_f32_e32 v34, v11, v34
	v_div_scale_f32 v11, vcc, v31, v26, v31
	v_mul_f32_e32 v16, v11, v34
	v_fma_f32 v32, -v12, v16, v11
	v_fmac_f32_e32 v16, v32, v34
	v_lshlrev_b32_e32 v32, 16, v67
	v_fma_f32 v11, -v12, v16, v11
	v_mul_f32_e32 v12, 0xbfb8aa3b, v32
	v_div_fmas_f32 v11, v11, v34, v16
	v_exp_f32_e32 v16, v12
	v_mul_f32_e32 v12, 0xbfb8aa3b, v33
	v_exp_f32_e32 v17, v12
	v_div_fixup_f32 v26, v11, v26, v31
	v_pk_mul_f32 v[24:25], v[24:25], v[26:27]
	v_lshlrev_b32_e32 v12, 16, v13
	v_pk_add_f32 v[16:17], v[16:17], 1.0 op_sel_hi:[1,0]
	v_and_b32_e32 v13, 0xffff0000, v13
	v_div_scale_f32 v26, s[0:1], v17, v17, v33
	v_rcp_f32_e32 v27, v26
	v_pk_mul_f32 v[10:11], v[10:11], v[12:13] op_sel_hi:[0,1]
	v_pk_mul_f32 v[10:11], v[4:5], v[10:11]
	v_fma_f32 v12, -v26, v27, 1.0
	v_fmac_f32_e32 v27, v12, v27
	v_div_scale_f32 v12, vcc, v33, v17, v33
	v_mul_f32_e32 v13, v12, v27
	v_fma_f32 v31, -v26, v13, v12
	v_fmac_f32_e32 v13, v31, v27
	v_fma_f32 v12, -v26, v13, v12
	v_div_scale_f32 v26, s[0:1], v16, v16, v32
	v_rcp_f32_e32 v31, v26
	v_div_fmas_f32 v12, v12, v27, v13
	v_div_fixup_f32 v13, v12, v17, v33
	v_fma_f32 v12, -v26, v31, 1.0
	v_fmac_f32_e32 v31, v12, v31
	v_div_scale_f32 v12, vcc, v32, v16, v32
	v_mul_f32_e32 v17, v12, v31
	v_fma_f32 v27, -v26, v17, v12
	v_fmac_f32_e32 v17, v27, v31
	v_fma_f32 v12, -v26, v17, v12
	v_div_fmas_f32 v12, v12, v31, v17
	v_div_fixup_f32 v12, v12, v16, v32
	v_pk_mul_f32 v[16:17], v[10:11], v[12:13]
	v_cvt_pk_bf16_f32 v10, v20, v21
	v_cvt_pk_bf16_f32 v11, v14, v15
	v_cvt_pk_bf16_f32 v12, v24, v25
	v_cvt_pk_bf16_f32 v13, v16, v17
	v_lshl_add_u64 v[14:15], s[36:37], 0, v[18:19]
	global_store_dwordx4 v[14:15], v[10:13], off sc1
	ds_read_b128 v[14:17], v29 offset:2112
	s_waitcnt lgkmcnt(0)
	v_lshlrev_b32_e32 v34, 16, v14
	v_or_b32_e32 v10, 4, v22
	v_mov_b32_e32 v11, v23
	v_lshlrev_b64 v[26:27], 11, v[10:11]
	v_or_b32_e32 v26, v26, v28
	v_lshl_add_u64 v[10:11], s[60:61], 0, v[26:27]
	v_and_b32_e32 v35, 0xffff0000, v14
	v_lshlrev_b32_e32 v31, 16, v68
	v_and_b32_e32 v18, 0xffff0000, v68
	v_mul_f32_e32 v10, 0xbfb8aa3b, v31
	v_exp_f32_e32 v32, v10
	v_mul_f32_e32 v10, 0xbfb8aa3b, v18
	v_exp_f32_e32 v33, v10
	ds_read2_b32 v[24:25], v30 offset0:132 offset1:134
	ds_read_b128 v[10:13], v29 offset:3168
	v_pk_add_f32 v[32:33], v[32:33], 1.0 op_sel_hi:[1,0]
	s_nop 0
	v_div_scale_f32 v36, s[0:1], v33, v33, v18
	v_rcp_f32_e32 v37, v36
	s_waitcnt lgkmcnt(1)
	v_pk_mul_f32 v[34:35], v[24:25], v[34:35] op_sel_hi:[0,1]
	v_pk_mul_f32 v[34:35], v[6:7], v[34:35]
	v_fma_f32 v14, -v36, v37, 1.0
	v_fmac_f32_e32 v37, v14, v37
	v_div_scale_f32 v14, vcc, v18, v33, v18
	v_mul_f32_e32 v38, v14, v37
	v_fma_f32 v39, -v36, v38, v14
	v_fmac_f32_e32 v38, v39, v37
	v_fma_f32 v14, -v36, v38, v14
	v_div_scale_f32 v36, s[0:1], v32, v32, v31
	v_rcp_f32_e32 v39, v36
	v_div_fmas_f32 v14, v14, v37, v38
	v_div_fixup_f32 v33, v14, v33, v18
	v_fma_f32 v14, -v36, v39, 1.0
	v_fmac_f32_e32 v39, v14, v39
	v_div_scale_f32 v14, vcc, v31, v32, v31
	v_mul_f32_e32 v18, v14, v39
	v_fma_f32 v37, -v36, v18, v14
	v_fmac_f32_e32 v18, v37, v39
	v_fma_f32 v14, -v36, v18, v14
	v_lshlrev_b32_e32 v36, 16, v69
	v_and_b32_e32 v37, 0xffff0000, v69
	v_div_fmas_f32 v14, v14, v39, v18
	v_mul_f32_e32 v18, 0xbfb8aa3b, v36
	v_mul_f32_e32 v19, 0xbfb8aa3b, v37
	v_exp_f32_e32 v18, v18
	v_exp_f32_e32 v19, v19
	v_div_fixup_f32 v32, v14, v32, v31
	v_pk_mul_f32 v[32:33], v[34:35], v[32:33]
	v_lshlrev_b32_e32 v14, 16, v15
	v_pk_add_f32 v[18:19], v[18:19], 1.0 op_sel_hi:[1,0]
	v_and_b32_e32 v15, 0xffff0000, v15
	v_div_scale_f32 v31, s[0:1], v19, v19, v37
	v_rcp_f32_e32 v34, v31
	v_pk_mul_f32 v[14:15], v[24:25], v[14:15] op_sel_hi:[0,1]
	v_pk_mul_f32 v[14:15], v[8:9], v[14:15]
	v_fma_f32 v35, -v31, v34, 1.0
	v_fmac_f32_e32 v34, v35, v34
	v_div_scale_f32 v35, vcc, v37, v19, v37
	v_mul_f32_e32 v38, v35, v34
	v_fma_f32 v39, -v31, v38, v35
	v_fmac_f32_e32 v38, v39, v34
	v_fma_f32 v31, -v31, v38, v35
	v_div_scale_f32 v35, s[0:1], v18, v18, v36
	v_rcp_f32_e32 v39, v35
	v_div_fmas_f32 v31, v31, v34, v38
	v_div_fixup_f32 v19, v31, v19, v37
	v_fma_f32 v31, -v35, v39, 1.0
	v_fmac_f32_e32 v39, v31, v39
	v_div_scale_f32 v31, vcc, v36, v18, v36
	v_mul_f32_e32 v34, v31, v39
	v_fma_f32 v37, -v35, v34, v31
	v_fmac_f32_e32 v34, v37, v39
	v_fma_f32 v31, -v35, v34, v31
	v_lshlrev_b32_e32 v37, 16, v70
	v_and_b32_e32 v20, 0xffff0000, v70
	v_div_fmas_f32 v31, v31, v39, v34
	v_mul_f32_e32 v34, 0xbfb8aa3b, v37
	v_mul_f32_e32 v35, 0xbfb8aa3b, v20
	v_exp_f32_e32 v34, v34
	v_exp_f32_e32 v35, v35
	v_div_fixup_f32 v18, v31, v18, v36
	v_pk_mul_f32 v[18:19], v[14:15], v[18:19]
	v_lshlrev_b32_e32 v14, 16, v16
	v_pk_add_f32 v[34:35], v[34:35], 1.0 op_sel_hi:[1,0]
	v_and_b32_e32 v15, 0xffff0000, v16
	v_div_scale_f32 v31, s[0:1], v35, v35, v20
	v_rcp_f32_e32 v36, v31
	v_pk_mul_f32 v[14:15], v[24:25], v[14:15] op_sel_hi:[0,1]
	v_pk_mul_f32 v[14:15], v[2:3], v[14:15]
	v_fma_f32 v16, -v31, v36, 1.0
	v_fmac_f32_e32 v36, v16, v36
	v_div_scale_f32 v16, vcc, v20, v35, v20
	v_mul_f32_e32 v38, v16, v36
	v_fma_f32 v39, -v31, v38, v16
	v_fmac_f32_e32 v38, v39, v36
	v_fma_f32 v16, -v31, v38, v16
	v_div_scale_f32 v31, s[0:1], v34, v34, v37
	v_rcp_f32_e32 v39, v31
	v_div_fmas_f32 v16, v16, v36, v38
	v_div_fixup_f32 v35, v16, v35, v20
	v_fma_f32 v16, -v31, v39, 1.0
	v_fmac_f32_e32 v39, v16, v39
	v_div_scale_f32 v16, vcc, v37, v34, v37
	v_mul_f32_e32 v20, v16, v39
	v_fma_f32 v36, -v31, v20, v16
	v_fmac_f32_e32 v20, v36, v39
	v_fma_f32 v16, -v31, v20, v16
	v_lshlrev_b32_e32 v31, 16, v71
	v_and_b32_e32 v36, 0xffff0000, v71
	v_div_fmas_f32 v16, v16, v39, v20
	v_mul_f32_e32 v20, 0xbfb8aa3b, v31
	v_mul_f32_e32 v21, 0xbfb8aa3b, v36
	v_exp_f32_e32 v20, v20
	v_exp_f32_e32 v21, v21
	v_div_fixup_f32 v34, v16, v34, v37
	v_pk_mul_f32 v[34:35], v[14:15], v[34:35]
	v_lshlrev_b32_e32 v14, 16, v17
	v_pk_add_f32 v[20:21], v[20:21], 1.0 op_sel_hi:[1,0]
	v_and_b32_e32 v15, 0xffff0000, v17
	v_div_scale_f32 v16, s[0:1], v21, v21, v36
	v_rcp_f32_e32 v37, v16
	v_pk_mul_f32 v[14:15], v[24:25], v[14:15] op_sel_hi:[0,1]
	v_pk_mul_f32 v[14:15], v[4:5], v[14:15]
	v_fma_f32 v17, -v16, v37, 1.0
	v_fmac_f32_e32 v37, v17, v37
	v_div_scale_f32 v17, vcc, v36, v21, v36
	v_mul_f32_e32 v24, v17, v37
	v_fma_f32 v38, -v16, v24, v17
	v_fmac_f32_e32 v24, v38, v37
	v_div_scale_f32 v38, s[0:1], v20, v20, v31
	v_rcp_f32_e32 v39, v38
	v_fma_f32 v16, -v16, v24, v17
	v_div_fmas_f32 v16, v16, v37, v24
	v_div_fixup_f32 v17, v16, v21, v36
	v_fma_f32 v16, -v38, v39, 1.0
	v_fmac_f32_e32 v39, v16, v39
	v_div_scale_f32 v16, vcc, v31, v20, v31
	v_mul_f32_e32 v21, v16, v39
	v_fma_f32 v24, -v38, v21, v16
	v_fmac_f32_e32 v21, v24, v39
	v_fma_f32 v16, -v38, v21, v16
	v_div_fmas_f32 v16, v16, v39, v21
	v_div_fixup_f32 v16, v16, v20, v31
	v_pk_mul_f32 v[20:21], v[14:15], v[16:17]
	v_cvt_pk_bf16_f32 v14, v32, v33
	v_cvt_pk_bf16_f32 v15, v18, v19
	v_cvt_pk_bf16_f32 v16, v34, v35
	v_cvt_pk_bf16_f32 v17, v20, v21
	v_lshl_add_u64 v[18:19], s[36:37], 0, v[26:27]
	global_store_dwordx4 v[18:19], v[14:17], off sc1
	s_waitcnt lgkmcnt(0)
	v_lshlrev_b32_e32 v26, 16, v10
	v_and_b32_e32 v27, 0xffff0000, v10
	v_or_b32_e32 v14, 6, v22
	v_mov_b32_e32 v15, v23
	v_lshlrev_b64 v[18:19], 11, v[14:15]
	v_or_b32_e32 v18, v18, v28
	v_lshl_add_u64 v[14:15], s[60:61], 0, v[18:19]
	v_mov_b32_e32 v10, v25
	v_pk_mul_f32 v[24:25], v[10:11], v[26:27] op_sel_hi:[0,1]
	v_pk_mul_f32 v[24:25], v[6:7], v[24:25]
	v_lshlrev_b32_e32 v31, 16, v72
	v_and_b32_e32 v14, 0xffff0000, v72
	v_mul_f32_e32 v20, 0xbfb8aa3b, v31
	v_mul_f32_e32 v21, 0xbfb8aa3b, v14
	v_exp_f32_e32 v20, v20
	v_exp_f32_e32 v21, v21
	s_nop 0
	v_pk_add_f32 v[20:21], v[20:21], 1.0 op_sel_hi:[1,0]
	s_nop 0
	v_div_scale_f32 v32, s[0:1], v21, v21, v14
	v_rcp_f32_e32 v33, v32
	s_nop 0
	v_fma_f32 v26, -v32, v33, 1.0
	v_fmac_f32_e32 v33, v26, v33
	v_div_scale_f32 v26, vcc, v14, v21, v14
	v_mul_f32_e32 v27, v26, v33
	v_fma_f32 v34, -v32, v27, v26
	v_fmac_f32_e32 v27, v34, v33
	v_fma_f32 v26, -v32, v27, v26
	v_div_scale_f32 v32, s[0:1], v20, v20, v31
	v_rcp_f32_e32 v34, v32
	v_div_fmas_f32 v26, v26, v33, v27
	v_div_fixup_f32 v21, v26, v21, v14
	v_fma_f32 v14, -v32, v34, 1.0
	v_fmac_f32_e32 v34, v14, v34
	v_div_scale_f32 v14, vcc, v31, v20, v31
	v_mul_f32_e32 v26, v14, v34
	v_fma_f32 v27, -v32, v26, v14
	v_fmac_f32_e32 v26, v27, v34
	v_fma_f32 v14, -v32, v26, v14
	v_lshlrev_b32_e32 v32, 16, v73
	v_and_b32_e32 v27, 0xffff0000, v73
	v_div_fmas_f32 v26, v14, v34, v26
	v_mul_f32_e32 v14, 0xbfb8aa3b, v32
	v_mul_f32_e32 v15, 0xbfb8aa3b, v27
	v_exp_f32_e32 v14, v14
	v_exp_f32_e32 v15, v15
	v_div_fixup_f32 v20, v26, v20, v31
	v_pk_mul_f32 v[20:21], v[24:25], v[20:21]
	v_lshlrev_b32_e32 v24, 16, v11
	v_pk_add_f32 v[14:15], v[14:15], 1.0 op_sel_hi:[1,0]
	v_and_b32_e32 v25, 0xffff0000, v11
	v_div_scale_f32 v26, s[0:1], v15, v15, v27
	v_rcp_f32_e32 v31, v26
	v_pk_mul_f32 v[24:25], v[10:11], v[24:25] op_sel_hi:[0,1]
	v_pk_mul_f32 v[24:25], v[8:9], v[24:25]
	v_fma_f32 v11, -v26, v31, 1.0
	v_fmac_f32_e32 v31, v11, v31
	v_div_scale_f32 v11, vcc, v27, v15, v27
	v_mul_f32_e32 v33, v11, v31
	v_fma_f32 v34, -v26, v33, v11
	v_fmac_f32_e32 v33, v34, v31
	v_fma_f32 v11, -v26, v33, v11
	v_div_scale_f32 v26, s[0:1], v14, v14, v32
	v_rcp_f32_e32 v34, v26
	v_div_fmas_f32 v11, v11, v31, v33
	v_div_fixup_f32 v15, v11, v15, v27
	v_fma_f32 v11, -v26, v34, 1.0
	v_fmac_f32_e32 v34, v11, v34
	v_div_scale_f32 v11, vcc, v32, v14, v32
	v_mul_f32_e32 v27, v11, v34
	v_fma_f32 v31, -v26, v27, v11
	v_fmac_f32_e32 v27, v31, v34
	v_fma_f32 v11, -v26, v27, v11
	v_lshlrev_b32_e32 v31, 16, v74
	v_and_b32_e32 v16, 0xffff0000, v74
	v_div_fmas_f32 v11, v11, v34, v27
	v_mul_f32_e32 v26, 0xbfb8aa3b, v31
	v_mul_f32_e32 v27, 0xbfb8aa3b, v16
	v_exp_f32_e32 v26, v26
	v_exp_f32_e32 v27, v27
	v_div_fixup_f32 v14, v11, v14, v32
	v_pk_mul_f32 v[14:15], v[24:25], v[14:15]
	v_lshlrev_b32_e32 v24, 16, v12
	v_pk_add_f32 v[26:27], v[26:27], 1.0 op_sel_hi:[1,0]
	v_and_b32_e32 v25, 0xffff0000, v12
	v_div_scale_f32 v11, s[0:1], v27, v27, v16
	v_rcp_f32_e32 v32, v11
	v_pk_mul_f32 v[24:25], v[10:11], v[24:25] op_sel_hi:[0,1]
	v_pk_mul_f32 v[24:25], v[2:3], v[24:25]
	v_fma_f32 v12, -v11, v32, 1.0
	v_fmac_f32_e32 v32, v12, v32
	v_div_scale_f32 v12, vcc, v16, v27, v16
	v_mul_f32_e32 v33, v12, v32
	v_fma_f32 v34, -v11, v33, v12
	v_fmac_f32_e32 v33, v34, v32
	v_fma_f32 v11, -v11, v33, v12
	v_div_scale_f32 v12, s[0:1], v26, v26, v31
	v_rcp_f32_e32 v34, v12
	v_div_fmas_f32 v11, v11, v32, v33
	v_div_fixup_f32 v27, v11, v27, v16
	v_and_b32_e32 v33, 0xffff0000, v75
	v_fma_f32 v11, -v12, v34, 1.0
	v_fmac_f32_e32 v34, v11, v34
	v_div_scale_f32 v11, vcc, v31, v26, v31
	v_mul_f32_e32 v16, v11, v34
	v_fma_f32 v32, -v12, v16, v11
	v_fmac_f32_e32 v16, v32, v34
	v_lshlrev_b32_e32 v32, 16, v75
	v_fma_f32 v11, -v12, v16, v11
	v_mul_f32_e32 v12, 0xbfb8aa3b, v32
	v_div_fmas_f32 v11, v11, v34, v16
	v_exp_f32_e32 v16, v12
	v_mul_f32_e32 v12, 0xbfb8aa3b, v33
	v_exp_f32_e32 v17, v12
	v_div_fixup_f32 v26, v11, v26, v31
	v_pk_mul_f32 v[24:25], v[24:25], v[26:27]
	v_lshlrev_b32_e32 v12, 16, v13
	v_pk_add_f32 v[16:17], v[16:17], 1.0 op_sel_hi:[1,0]
	v_and_b32_e32 v13, 0xffff0000, v13
	v_div_scale_f32 v26, s[0:1], v17, v17, v33
	v_rcp_f32_e32 v27, v26
	v_pk_mul_f32 v[10:11], v[10:11], v[12:13] op_sel_hi:[0,1]
	v_pk_mul_f32 v[10:11], v[4:5], v[10:11]
	v_fma_f32 v12, -v26, v27, 1.0
	v_fmac_f32_e32 v27, v12, v27
	v_div_scale_f32 v12, vcc, v33, v17, v33
	v_mul_f32_e32 v13, v12, v27
	v_fma_f32 v31, -v26, v13, v12
	v_fmac_f32_e32 v13, v31, v27
	v_fma_f32 v12, -v26, v13, v12
	v_div_scale_f32 v26, s[0:1], v16, v16, v32
	v_rcp_f32_e32 v31, v26
	v_div_fmas_f32 v12, v12, v27, v13
	v_div_fixup_f32 v13, v12, v17, v33
	v_fma_f32 v12, -v26, v31, 1.0
	v_fmac_f32_e32 v31, v12, v31
	v_div_scale_f32 v12, vcc, v32, v16, v32
	v_mul_f32_e32 v17, v12, v31
	v_fma_f32 v27, -v26, v17, v12
	v_fmac_f32_e32 v17, v27, v31
	v_fma_f32 v12, -v26, v17, v12
	v_div_fmas_f32 v12, v12, v31, v17
	v_div_fixup_f32 v12, v12, v16, v32
	v_pk_mul_f32 v[16:17], v[10:11], v[12:13]
	v_cvt_pk_bf16_f32 v10, v20, v21
	v_cvt_pk_bf16_f32 v11, v14, v15
	v_cvt_pk_bf16_f32 v12, v24, v25
	v_cvt_pk_bf16_f32 v13, v16, v17
	v_lshl_add_u64 v[14:15], s[36:37], 0, v[18:19]
	global_store_dwordx4 v[14:15], v[10:13], off sc1
	ds_read_b128 v[14:17], v29 offset:4224
	s_waitcnt lgkmcnt(0)
	v_lshlrev_b32_e32 v34, 16, v14
	v_or_b32_e32 v10, 8, v22
	v_mov_b32_e32 v11, v23
	v_lshlrev_b64 v[26:27], 11, v[10:11]
	v_or_b32_e32 v26, v26, v28
	v_lshl_add_u64 v[10:11], s[60:61], 0, v[26:27]
	v_and_b32_e32 v35, 0xffff0000, v14
	v_lshlrev_b32_e32 v31, 16, v76
	v_and_b32_e32 v18, 0xffff0000, v76
	v_mul_f32_e32 v10, 0xbfb8aa3b, v31
	v_exp_f32_e32 v32, v10
	v_mul_f32_e32 v10, 0xbfb8aa3b, v18
	v_exp_f32_e32 v33, v10
	ds_read2_b32 v[24:25], v30 offset0:136 offset1:138
	ds_read_b128 v[10:13], v29 offset:5280
	v_pk_add_f32 v[32:33], v[32:33], 1.0 op_sel_hi:[1,0]
	s_nop 0
	v_div_scale_f32 v36, s[0:1], v33, v33, v18
	v_rcp_f32_e32 v37, v36
	s_waitcnt lgkmcnt(1)
	v_pk_mul_f32 v[34:35], v[24:25], v[34:35] op_sel_hi:[0,1]
	v_pk_mul_f32 v[34:35], v[6:7], v[34:35]
	v_fma_f32 v14, -v36, v37, 1.0
	v_fmac_f32_e32 v37, v14, v37
	v_div_scale_f32 v14, vcc, v18, v33, v18
	v_mul_f32_e32 v38, v14, v37
	v_fma_f32 v39, -v36, v38, v14
	v_fmac_f32_e32 v38, v39, v37
	v_fma_f32 v14, -v36, v38, v14
	v_div_scale_f32 v36, s[0:1], v32, v32, v31
	v_rcp_f32_e32 v39, v36
	v_div_fmas_f32 v14, v14, v37, v38
	v_div_fixup_f32 v33, v14, v33, v18
	v_fma_f32 v14, -v36, v39, 1.0
	v_fmac_f32_e32 v39, v14, v39
	v_div_scale_f32 v14, vcc, v31, v32, v31
	v_mul_f32_e32 v18, v14, v39
	v_fma_f32 v37, -v36, v18, v14
	v_fmac_f32_e32 v18, v37, v39
	v_fma_f32 v14, -v36, v18, v14
	v_lshlrev_b32_e32 v36, 16, v77
	v_and_b32_e32 v37, 0xffff0000, v77
	v_div_fmas_f32 v14, v14, v39, v18
	v_mul_f32_e32 v18, 0xbfb8aa3b, v36
	v_mul_f32_e32 v19, 0xbfb8aa3b, v37
	v_exp_f32_e32 v18, v18
	v_exp_f32_e32 v19, v19
	v_div_fixup_f32 v32, v14, v32, v31
	v_pk_mul_f32 v[32:33], v[34:35], v[32:33]
	v_lshlrev_b32_e32 v14, 16, v15
	v_pk_add_f32 v[18:19], v[18:19], 1.0 op_sel_hi:[1,0]
	v_and_b32_e32 v15, 0xffff0000, v15
	v_div_scale_f32 v31, s[0:1], v19, v19, v37
	v_rcp_f32_e32 v34, v31
	v_pk_mul_f32 v[14:15], v[24:25], v[14:15] op_sel_hi:[0,1]
	v_pk_mul_f32 v[14:15], v[8:9], v[14:15]
	v_fma_f32 v35, -v31, v34, 1.0
	v_fmac_f32_e32 v34, v35, v34
	v_div_scale_f32 v35, vcc, v37, v19, v37
	v_mul_f32_e32 v38, v35, v34
	v_fma_f32 v39, -v31, v38, v35
	v_fmac_f32_e32 v38, v39, v34
	v_fma_f32 v31, -v31, v38, v35
	v_div_scale_f32 v35, s[0:1], v18, v18, v36
	v_rcp_f32_e32 v39, v35
	v_div_fmas_f32 v31, v31, v34, v38
	v_div_fixup_f32 v19, v31, v19, v37
	v_fma_f32 v31, -v35, v39, 1.0
	v_fmac_f32_e32 v39, v31, v39
	v_div_scale_f32 v31, vcc, v36, v18, v36
	v_mul_f32_e32 v34, v31, v39
	v_fma_f32 v37, -v35, v34, v31
	v_fmac_f32_e32 v34, v37, v39
	v_fma_f32 v31, -v35, v34, v31
	v_lshlrev_b32_e32 v37, 16, v78
	v_and_b32_e32 v20, 0xffff0000, v78
	v_div_fmas_f32 v31, v31, v39, v34
	v_mul_f32_e32 v34, 0xbfb8aa3b, v37
	v_mul_f32_e32 v35, 0xbfb8aa3b, v20
	v_exp_f32_e32 v34, v34
	v_exp_f32_e32 v35, v35
	v_div_fixup_f32 v18, v31, v18, v36
	v_pk_mul_f32 v[18:19], v[14:15], v[18:19]
	v_lshlrev_b32_e32 v14, 16, v16
	v_pk_add_f32 v[34:35], v[34:35], 1.0 op_sel_hi:[1,0]
	v_and_b32_e32 v15, 0xffff0000, v16
	v_div_scale_f32 v31, s[0:1], v35, v35, v20
	v_rcp_f32_e32 v36, v31
	v_pk_mul_f32 v[14:15], v[24:25], v[14:15] op_sel_hi:[0,1]
	v_pk_mul_f32 v[14:15], v[2:3], v[14:15]
	v_fma_f32 v16, -v31, v36, 1.0
	v_fmac_f32_e32 v36, v16, v36
	v_div_scale_f32 v16, vcc, v20, v35, v20
	v_mul_f32_e32 v38, v16, v36
	v_fma_f32 v39, -v31, v38, v16
	v_fmac_f32_e32 v38, v39, v36
	v_fma_f32 v16, -v31, v38, v16
	v_div_scale_f32 v31, s[0:1], v34, v34, v37
	v_rcp_f32_e32 v39, v31
	v_div_fmas_f32 v16, v16, v36, v38
	v_div_fixup_f32 v35, v16, v35, v20
	v_fma_f32 v16, -v31, v39, 1.0
	v_fmac_f32_e32 v39, v16, v39
	v_div_scale_f32 v16, vcc, v37, v34, v37
	v_mul_f32_e32 v20, v16, v39
	v_fma_f32 v36, -v31, v20, v16
	v_fmac_f32_e32 v20, v36, v39
	v_fma_f32 v16, -v31, v20, v16
	v_lshlrev_b32_e32 v31, 16, v79
	v_and_b32_e32 v36, 0xffff0000, v79
	v_div_fmas_f32 v16, v16, v39, v20
	v_mul_f32_e32 v20, 0xbfb8aa3b, v31
	v_mul_f32_e32 v21, 0xbfb8aa3b, v36
	v_exp_f32_e32 v20, v20
	v_exp_f32_e32 v21, v21
	v_div_fixup_f32 v34, v16, v34, v37
	v_pk_mul_f32 v[34:35], v[14:15], v[34:35]
	v_lshlrev_b32_e32 v14, 16, v17
	v_pk_add_f32 v[20:21], v[20:21], 1.0 op_sel_hi:[1,0]
	v_and_b32_e32 v15, 0xffff0000, v17
	v_div_scale_f32 v16, s[0:1], v21, v21, v36
	v_rcp_f32_e32 v37, v16
	v_pk_mul_f32 v[14:15], v[24:25], v[14:15] op_sel_hi:[0,1]
	v_pk_mul_f32 v[14:15], v[4:5], v[14:15]
	v_fma_f32 v17, -v16, v37, 1.0
	v_fmac_f32_e32 v37, v17, v37
	v_div_scale_f32 v17, vcc, v36, v21, v36
	v_mul_f32_e32 v24, v17, v37
	v_fma_f32 v38, -v16, v24, v17
	v_fmac_f32_e32 v24, v38, v37
	v_div_scale_f32 v38, s[0:1], v20, v20, v31
	v_rcp_f32_e32 v39, v38
	v_fma_f32 v16, -v16, v24, v17
	v_div_fmas_f32 v16, v16, v37, v24
	v_div_fixup_f32 v17, v16, v21, v36
	v_fma_f32 v16, -v38, v39, 1.0
	v_fmac_f32_e32 v39, v16, v39
	v_div_scale_f32 v16, vcc, v31, v20, v31
	v_mul_f32_e32 v21, v16, v39
	v_fma_f32 v24, -v38, v21, v16
	v_fmac_f32_e32 v21, v24, v39
	v_fma_f32 v16, -v38, v21, v16
	v_div_fmas_f32 v16, v16, v39, v21
	v_div_fixup_f32 v16, v16, v20, v31
	v_pk_mul_f32 v[20:21], v[14:15], v[16:17]
	v_cvt_pk_bf16_f32 v14, v32, v33
	v_cvt_pk_bf16_f32 v15, v18, v19
	v_cvt_pk_bf16_f32 v16, v34, v35
	v_cvt_pk_bf16_f32 v17, v20, v21
	v_lshl_add_u64 v[18:19], s[36:37], 0, v[26:27]
	global_store_dwordx4 v[18:19], v[14:17], off sc1
	s_waitcnt lgkmcnt(0)
	v_lshlrev_b32_e32 v26, 16, v10
	v_and_b32_e32 v27, 0xffff0000, v10
	v_or_b32_e32 v14, 10, v22
	v_mov_b32_e32 v15, v23
	v_lshlrev_b64 v[18:19], 11, v[14:15]
	v_or_b32_e32 v18, v18, v28
	v_lshl_add_u64 v[14:15], s[60:61], 0, v[18:19]
	v_mov_b32_e32 v10, v25
	v_pk_mul_f32 v[24:25], v[10:11], v[26:27] op_sel_hi:[0,1]
	v_pk_mul_f32 v[24:25], v[6:7], v[24:25]
	v_lshlrev_b32_e32 v31, 16, v80
	v_and_b32_e32 v14, 0xffff0000, v80
	v_mul_f32_e32 v20, 0xbfb8aa3b, v31
	v_mul_f32_e32 v21, 0xbfb8aa3b, v14
	v_exp_f32_e32 v20, v20
	v_exp_f32_e32 v21, v21
	s_nop 0
	v_pk_add_f32 v[20:21], v[20:21], 1.0 op_sel_hi:[1,0]
	s_nop 0
	v_div_scale_f32 v32, s[0:1], v21, v21, v14
	v_rcp_f32_e32 v33, v32
	s_nop 0
	v_fma_f32 v26, -v32, v33, 1.0
	v_fmac_f32_e32 v33, v26, v33
	v_div_scale_f32 v26, vcc, v14, v21, v14
	v_mul_f32_e32 v27, v26, v33
	v_fma_f32 v34, -v32, v27, v26
	v_fmac_f32_e32 v27, v34, v33
	v_fma_f32 v26, -v32, v27, v26
	v_div_scale_f32 v32, s[0:1], v20, v20, v31
	v_rcp_f32_e32 v34, v32
	v_div_fmas_f32 v26, v26, v33, v27
	v_div_fixup_f32 v21, v26, v21, v14
	v_fma_f32 v14, -v32, v34, 1.0
	v_fmac_f32_e32 v34, v14, v34
	v_div_scale_f32 v14, vcc, v31, v20, v31
	v_mul_f32_e32 v26, v14, v34
	v_fma_f32 v27, -v32, v26, v14
	v_fmac_f32_e32 v26, v27, v34
	v_fma_f32 v14, -v32, v26, v14
	v_lshlrev_b32_e32 v32, 16, v81
	v_and_b32_e32 v27, 0xffff0000, v81
	v_div_fmas_f32 v26, v14, v34, v26
	v_mul_f32_e32 v14, 0xbfb8aa3b, v32
	v_mul_f32_e32 v15, 0xbfb8aa3b, v27
	v_exp_f32_e32 v14, v14
	v_exp_f32_e32 v15, v15
	v_div_fixup_f32 v20, v26, v20, v31
	v_pk_mul_f32 v[20:21], v[24:25], v[20:21]
	v_lshlrev_b32_e32 v24, 16, v11
	v_pk_add_f32 v[14:15], v[14:15], 1.0 op_sel_hi:[1,0]
	v_and_b32_e32 v25, 0xffff0000, v11
	v_div_scale_f32 v26, s[0:1], v15, v15, v27
	v_rcp_f32_e32 v31, v26
	v_pk_mul_f32 v[24:25], v[10:11], v[24:25] op_sel_hi:[0,1]
	v_pk_mul_f32 v[24:25], v[8:9], v[24:25]
	v_fma_f32 v11, -v26, v31, 1.0
	v_fmac_f32_e32 v31, v11, v31
	v_div_scale_f32 v11, vcc, v27, v15, v27
	v_mul_f32_e32 v33, v11, v31
	v_fma_f32 v34, -v26, v33, v11
	v_fmac_f32_e32 v33, v34, v31
	v_fma_f32 v11, -v26, v33, v11
	v_div_scale_f32 v26, s[0:1], v14, v14, v32
	v_rcp_f32_e32 v34, v26
	v_div_fmas_f32 v11, v11, v31, v33
	v_div_fixup_f32 v15, v11, v15, v27
	v_fma_f32 v11, -v26, v34, 1.0
	v_fmac_f32_e32 v34, v11, v34
	v_div_scale_f32 v11, vcc, v32, v14, v32
	v_mul_f32_e32 v27, v11, v34
	v_fma_f32 v31, -v26, v27, v11
	v_fmac_f32_e32 v27, v31, v34
	v_fma_f32 v11, -v26, v27, v11
	v_lshlrev_b32_e32 v31, 16, v82
	v_and_b32_e32 v16, 0xffff0000, v82
	v_div_fmas_f32 v11, v11, v34, v27
	v_mul_f32_e32 v26, 0xbfb8aa3b, v31
	v_mul_f32_e32 v27, 0xbfb8aa3b, v16
	v_exp_f32_e32 v26, v26
	v_exp_f32_e32 v27, v27
	v_div_fixup_f32 v14, v11, v14, v32
	v_pk_mul_f32 v[14:15], v[24:25], v[14:15]
	v_lshlrev_b32_e32 v24, 16, v12
	v_pk_add_f32 v[26:27], v[26:27], 1.0 op_sel_hi:[1,0]
	v_and_b32_e32 v25, 0xffff0000, v12
	v_div_scale_f32 v11, s[0:1], v27, v27, v16
	v_rcp_f32_e32 v32, v11
	v_pk_mul_f32 v[24:25], v[10:11], v[24:25] op_sel_hi:[0,1]
	v_pk_mul_f32 v[24:25], v[2:3], v[24:25]
	v_fma_f32 v12, -v11, v32, 1.0
	v_fmac_f32_e32 v32, v12, v32
	v_div_scale_f32 v12, vcc, v16, v27, v16
	v_mul_f32_e32 v33, v12, v32
	v_fma_f32 v34, -v11, v33, v12
	v_fmac_f32_e32 v33, v34, v32
	v_fma_f32 v11, -v11, v33, v12
	v_div_scale_f32 v12, s[0:1], v26, v26, v31
	v_rcp_f32_e32 v34, v12
	v_div_fmas_f32 v11, v11, v32, v33
	v_div_fixup_f32 v27, v11, v27, v16
	v_and_b32_e32 v33, 0xffff0000, v83
	v_fma_f32 v11, -v12, v34, 1.0
	v_fmac_f32_e32 v34, v11, v34
	v_div_scale_f32 v11, vcc, v31, v26, v31
	v_mul_f32_e32 v16, v11, v34
	v_fma_f32 v32, -v12, v16, v11
	v_fmac_f32_e32 v16, v32, v34
	v_lshlrev_b32_e32 v32, 16, v83
	v_fma_f32 v11, -v12, v16, v11
	v_mul_f32_e32 v12, 0xbfb8aa3b, v32
	v_div_fmas_f32 v11, v11, v34, v16
	v_exp_f32_e32 v16, v12
	v_mul_f32_e32 v12, 0xbfb8aa3b, v33
	v_exp_f32_e32 v17, v12
	v_div_fixup_f32 v26, v11, v26, v31
	v_pk_mul_f32 v[24:25], v[24:25], v[26:27]
	v_lshlrev_b32_e32 v12, 16, v13
	v_pk_add_f32 v[16:17], v[16:17], 1.0 op_sel_hi:[1,0]
	v_and_b32_e32 v13, 0xffff0000, v13
	v_div_scale_f32 v26, s[0:1], v17, v17, v33
	v_rcp_f32_e32 v27, v26
	v_pk_mul_f32 v[10:11], v[10:11], v[12:13] op_sel_hi:[0,1]
	v_pk_mul_f32 v[10:11], v[4:5], v[10:11]
	v_fma_f32 v12, -v26, v27, 1.0
	v_fmac_f32_e32 v27, v12, v27
	v_div_scale_f32 v12, vcc, v33, v17, v33
	v_mul_f32_e32 v13, v12, v27
	v_fma_f32 v31, -v26, v13, v12
	v_fmac_f32_e32 v13, v31, v27
	v_fma_f32 v12, -v26, v13, v12
	v_div_scale_f32 v26, s[0:1], v16, v16, v32
	v_rcp_f32_e32 v31, v26
	v_div_fmas_f32 v12, v12, v27, v13
	v_div_fixup_f32 v13, v12, v17, v33
	v_fma_f32 v12, -v26, v31, 1.0
	v_fmac_f32_e32 v31, v12, v31
	v_div_scale_f32 v12, vcc, v32, v16, v32
	v_mul_f32_e32 v17, v12, v31
	v_fma_f32 v27, -v26, v17, v12
	v_fmac_f32_e32 v17, v27, v31
	v_fma_f32 v12, -v26, v17, v12
	v_div_fmas_f32 v12, v12, v31, v17
	v_div_fixup_f32 v12, v12, v16, v32
	v_pk_mul_f32 v[16:17], v[10:11], v[12:13]
	v_cvt_pk_bf16_f32 v10, v20, v21
	v_cvt_pk_bf16_f32 v11, v14, v15
	v_cvt_pk_bf16_f32 v12, v24, v25
	v_cvt_pk_bf16_f32 v13, v16, v17
	v_lshl_add_u64 v[14:15], s[36:37], 0, v[18:19]
	global_store_dwordx4 v[14:15], v[10:13], off sc1
	ds_read_b128 v[14:17], v29 offset:6336
	s_waitcnt lgkmcnt(0)
	v_lshlrev_b32_e32 v34, 16, v14
	v_or_b32_e32 v10, 12, v22
	v_mov_b32_e32 v11, v23
	v_lshlrev_b64 v[26:27], 11, v[10:11]
	v_or_b32_e32 v26, v26, v28
	v_lshl_add_u64 v[10:11], s[60:61], 0, v[26:27]
	v_and_b32_e32 v35, 0xffff0000, v14
	v_lshlrev_b32_e32 v31, 16, v84
	v_and_b32_e32 v18, 0xffff0000, v84
	v_mul_f32_e32 v10, 0xbfb8aa3b, v31
	v_exp_f32_e32 v32, v10
	v_mul_f32_e32 v10, 0xbfb8aa3b, v18
	v_exp_f32_e32 v33, v10
	ds_read2_b32 v[24:25], v30 offset0:140 offset1:142
	ds_read_b128 v[10:13], v29 offset:7392
	v_pk_add_f32 v[32:33], v[32:33], 1.0 op_sel_hi:[1,0]
	s_nop 0
	v_div_scale_f32 v36, s[0:1], v33, v33, v18
	v_rcp_f32_e32 v37, v36
	s_waitcnt lgkmcnt(1)
	v_pk_mul_f32 v[34:35], v[24:25], v[34:35] op_sel_hi:[0,1]
	v_pk_mul_f32 v[34:35], v[6:7], v[34:35]
	v_fma_f32 v14, -v36, v37, 1.0
	v_fmac_f32_e32 v37, v14, v37
	v_div_scale_f32 v14, vcc, v18, v33, v18
	v_mul_f32_e32 v38, v14, v37
	v_fma_f32 v39, -v36, v38, v14
	v_fmac_f32_e32 v38, v39, v37
	v_fma_f32 v14, -v36, v38, v14
	v_div_scale_f32 v36, s[0:1], v32, v32, v31
	v_rcp_f32_e32 v39, v36
	v_div_fmas_f32 v14, v14, v37, v38
	v_div_fixup_f32 v33, v14, v33, v18
	v_fma_f32 v14, -v36, v39, 1.0
	v_fmac_f32_e32 v39, v14, v39
	v_div_scale_f32 v14, vcc, v31, v32, v31
	v_mul_f32_e32 v18, v14, v39
	v_fma_f32 v37, -v36, v18, v14
	v_fmac_f32_e32 v18, v37, v39
	v_fma_f32 v14, -v36, v18, v14
	v_lshlrev_b32_e32 v36, 16, v85
	v_and_b32_e32 v37, 0xffff0000, v85
	v_div_fmas_f32 v14, v14, v39, v18
	v_mul_f32_e32 v18, 0xbfb8aa3b, v36
	v_mul_f32_e32 v19, 0xbfb8aa3b, v37
	v_exp_f32_e32 v18, v18
	v_exp_f32_e32 v19, v19
	v_div_fixup_f32 v32, v14, v32, v31
	v_pk_mul_f32 v[32:33], v[34:35], v[32:33]
	v_lshlrev_b32_e32 v14, 16, v15
	v_pk_add_f32 v[18:19], v[18:19], 1.0 op_sel_hi:[1,0]
	v_and_b32_e32 v15, 0xffff0000, v15
	v_div_scale_f32 v31, s[0:1], v19, v19, v37
	v_rcp_f32_e32 v34, v31
	v_pk_mul_f32 v[14:15], v[24:25], v[14:15] op_sel_hi:[0,1]
	v_pk_mul_f32 v[14:15], v[8:9], v[14:15]
	v_fma_f32 v35, -v31, v34, 1.0
	v_fmac_f32_e32 v34, v35, v34
	v_div_scale_f32 v35, vcc, v37, v19, v37
	v_mul_f32_e32 v38, v35, v34
	v_fma_f32 v39, -v31, v38, v35
	v_fmac_f32_e32 v38, v39, v34
	v_fma_f32 v31, -v31, v38, v35
	v_div_scale_f32 v35, s[0:1], v18, v18, v36
	v_rcp_f32_e32 v39, v35
	v_div_fmas_f32 v31, v31, v34, v38
	v_div_fixup_f32 v19, v31, v19, v37
	v_fma_f32 v31, -v35, v39, 1.0
	v_fmac_f32_e32 v39, v31, v39
	v_div_scale_f32 v31, vcc, v36, v18, v36
	v_mul_f32_e32 v34, v31, v39
	v_fma_f32 v37, -v35, v34, v31
	v_fmac_f32_e32 v34, v37, v39
	v_fma_f32 v31, -v35, v34, v31
	v_lshlrev_b32_e32 v37, 16, v86
	v_and_b32_e32 v20, 0xffff0000, v86
	v_div_fmas_f32 v31, v31, v39, v34
	v_mul_f32_e32 v34, 0xbfb8aa3b, v37
	v_mul_f32_e32 v35, 0xbfb8aa3b, v20
	v_exp_f32_e32 v34, v34
	v_exp_f32_e32 v35, v35
	v_div_fixup_f32 v18, v31, v18, v36
	v_pk_mul_f32 v[18:19], v[14:15], v[18:19]
	v_lshlrev_b32_e32 v14, 16, v16
	v_pk_add_f32 v[34:35], v[34:35], 1.0 op_sel_hi:[1,0]
	v_and_b32_e32 v15, 0xffff0000, v16
	v_div_scale_f32 v31, s[0:1], v35, v35, v20
	v_rcp_f32_e32 v36, v31
	v_pk_mul_f32 v[14:15], v[24:25], v[14:15] op_sel_hi:[0,1]
	v_pk_mul_f32 v[14:15], v[2:3], v[14:15]
	v_fma_f32 v16, -v31, v36, 1.0
	v_fmac_f32_e32 v36, v16, v36
	v_div_scale_f32 v16, vcc, v20, v35, v20
	v_mul_f32_e32 v38, v16, v36
	v_fma_f32 v39, -v31, v38, v16
	v_fmac_f32_e32 v38, v39, v36
	v_fma_f32 v16, -v31, v38, v16
	v_div_scale_f32 v31, s[0:1], v34, v34, v37
	v_rcp_f32_e32 v39, v31
	v_div_fmas_f32 v16, v16, v36, v38
	v_div_fixup_f32 v35, v16, v35, v20
	v_fma_f32 v16, -v31, v39, 1.0
	v_fmac_f32_e32 v39, v16, v39
	v_div_scale_f32 v16, vcc, v37, v34, v37
	v_mul_f32_e32 v20, v16, v39
	v_fma_f32 v36, -v31, v20, v16
	v_fmac_f32_e32 v20, v36, v39
	v_fma_f32 v16, -v31, v20, v16
	v_lshlrev_b32_e32 v31, 16, v87
	v_and_b32_e32 v36, 0xffff0000, v87
	v_div_fmas_f32 v16, v16, v39, v20
	v_mul_f32_e32 v20, 0xbfb8aa3b, v31
	v_mul_f32_e32 v21, 0xbfb8aa3b, v36
	v_exp_f32_e32 v20, v20
	v_exp_f32_e32 v21, v21
	v_div_fixup_f32 v34, v16, v34, v37
	v_pk_mul_f32 v[34:35], v[14:15], v[34:35]
	v_lshlrev_b32_e32 v14, 16, v17
	v_pk_add_f32 v[20:21], v[20:21], 1.0 op_sel_hi:[1,0]
	v_and_b32_e32 v15, 0xffff0000, v17
	v_div_scale_f32 v16, s[0:1], v21, v21, v36
	v_rcp_f32_e32 v37, v16
	v_pk_mul_f32 v[14:15], v[24:25], v[14:15] op_sel_hi:[0,1]
	v_pk_mul_f32 v[14:15], v[4:5], v[14:15]
	v_fma_f32 v17, -v16, v37, 1.0
	v_fmac_f32_e32 v37, v17, v37
	v_div_scale_f32 v17, vcc, v36, v21, v36
	v_mul_f32_e32 v24, v17, v37
	v_fma_f32 v38, -v16, v24, v17
	v_fmac_f32_e32 v24, v38, v37
	v_div_scale_f32 v38, s[0:1], v20, v20, v31
	v_rcp_f32_e32 v39, v38
	v_fma_f32 v16, -v16, v24, v17
	v_div_fmas_f32 v16, v16, v37, v24
	v_div_fixup_f32 v17, v16, v21, v36
	v_fma_f32 v16, -v38, v39, 1.0
	v_fmac_f32_e32 v39, v16, v39
	v_div_scale_f32 v16, vcc, v31, v20, v31
	v_mul_f32_e32 v21, v16, v39
	v_fma_f32 v24, -v38, v21, v16
	v_fmac_f32_e32 v21, v24, v39
	v_fma_f32 v16, -v38, v21, v16
	v_div_fmas_f32 v16, v16, v39, v21
	v_div_fixup_f32 v16, v16, v20, v31
	v_pk_mul_f32 v[20:21], v[14:15], v[16:17]
	v_cvt_pk_bf16_f32 v14, v32, v33
	v_cvt_pk_bf16_f32 v15, v18, v19
	v_cvt_pk_bf16_f32 v16, v34, v35
	v_cvt_pk_bf16_f32 v17, v20, v21
	v_lshl_add_u64 v[18:19], s[36:37], 0, v[26:27]
	global_store_dwordx4 v[18:19], v[14:17], off sc1
	s_waitcnt lgkmcnt(0)
	v_lshlrev_b32_e32 v26, 16, v10
	v_and_b32_e32 v27, 0xffff0000, v10
	v_or_b32_e32 v14, 14, v22
	v_mov_b32_e32 v15, v23
	v_lshlrev_b64 v[18:19], 11, v[14:15]
	v_or_b32_e32 v18, v18, v28
	v_lshl_add_u64 v[14:15], s[60:61], 0, v[18:19]
	v_mov_b32_e32 v10, v25
	v_pk_mul_f32 v[24:25], v[10:11], v[26:27] op_sel_hi:[0,1]
	v_pk_mul_f32 v[24:25], v[6:7], v[24:25]
	v_lshlrev_b32_e32 v31, 16, v88
	v_and_b32_e32 v14, 0xffff0000, v88
	v_mul_f32_e32 v20, 0xbfb8aa3b, v31
	v_mul_f32_e32 v21, 0xbfb8aa3b, v14
	v_exp_f32_e32 v20, v20
	v_exp_f32_e32 v21, v21
	s_nop 0
	v_pk_add_f32 v[20:21], v[20:21], 1.0 op_sel_hi:[1,0]
	s_nop 0
	v_div_scale_f32 v32, s[0:1], v21, v21, v14
	v_rcp_f32_e32 v33, v32
	s_nop 0
	v_fma_f32 v26, -v32, v33, 1.0
	v_fmac_f32_e32 v33, v26, v33
	v_div_scale_f32 v26, vcc, v14, v21, v14
	v_mul_f32_e32 v27, v26, v33
	v_fma_f32 v34, -v32, v27, v26
	v_fmac_f32_e32 v27, v34, v33
	v_fma_f32 v26, -v32, v27, v26
	v_div_scale_f32 v32, s[0:1], v20, v20, v31
	v_rcp_f32_e32 v34, v32
	v_div_fmas_f32 v26, v26, v33, v27
	v_div_fixup_f32 v21, v26, v21, v14
	v_fma_f32 v14, -v32, v34, 1.0
	v_fmac_f32_e32 v34, v14, v34
	v_div_scale_f32 v14, vcc, v31, v20, v31
	v_mul_f32_e32 v26, v14, v34
	v_fma_f32 v27, -v32, v26, v14
	v_fmac_f32_e32 v26, v27, v34
	v_fma_f32 v14, -v32, v26, v14
	v_lshlrev_b32_e32 v32, 16, v89
	v_and_b32_e32 v27, 0xffff0000, v89
	v_div_fmas_f32 v26, v14, v34, v26
	v_mul_f32_e32 v14, 0xbfb8aa3b, v32
	v_mul_f32_e32 v15, 0xbfb8aa3b, v27
	v_exp_f32_e32 v14, v14
	v_exp_f32_e32 v15, v15
	v_div_fixup_f32 v20, v26, v20, v31
	v_pk_mul_f32 v[20:21], v[24:25], v[20:21]
	v_lshlrev_b32_e32 v24, 16, v11
	v_pk_add_f32 v[14:15], v[14:15], 1.0 op_sel_hi:[1,0]
	v_and_b32_e32 v25, 0xffff0000, v11
	v_div_scale_f32 v26, s[0:1], v15, v15, v27
	v_rcp_f32_e32 v31, v26
	v_pk_mul_f32 v[24:25], v[10:11], v[24:25] op_sel_hi:[0,1]
	v_pk_mul_f32 v[24:25], v[8:9], v[24:25]
	v_fma_f32 v11, -v26, v31, 1.0
	v_fmac_f32_e32 v31, v11, v31
	v_div_scale_f32 v11, vcc, v27, v15, v27
	v_mul_f32_e32 v33, v11, v31
	v_fma_f32 v34, -v26, v33, v11
	v_fmac_f32_e32 v33, v34, v31
	v_fma_f32 v11, -v26, v33, v11
	v_div_scale_f32 v26, s[0:1], v14, v14, v32
	v_rcp_f32_e32 v34, v26
	v_div_fmas_f32 v11, v11, v31, v33
	v_div_fixup_f32 v15, v11, v15, v27
	v_fma_f32 v11, -v26, v34, 1.0
	v_fmac_f32_e32 v34, v11, v34
	v_div_scale_f32 v11, vcc, v32, v14, v32
	v_mul_f32_e32 v27, v11, v34
	v_fma_f32 v31, -v26, v27, v11
	v_fmac_f32_e32 v27, v31, v34
	v_fma_f32 v11, -v26, v27, v11
	v_lshlrev_b32_e32 v31, 16, v90
	v_and_b32_e32 v16, 0xffff0000, v90
	v_div_fmas_f32 v11, v11, v34, v27
	v_mul_f32_e32 v26, 0xbfb8aa3b, v31
	v_mul_f32_e32 v27, 0xbfb8aa3b, v16
	v_exp_f32_e32 v26, v26
	v_exp_f32_e32 v27, v27
	v_div_fixup_f32 v14, v11, v14, v32
	v_pk_mul_f32 v[14:15], v[24:25], v[14:15]
	v_lshlrev_b32_e32 v24, 16, v12
	v_pk_add_f32 v[26:27], v[26:27], 1.0 op_sel_hi:[1,0]
	v_and_b32_e32 v25, 0xffff0000, v12
	v_div_scale_f32 v11, s[0:1], v27, v27, v16
	v_rcp_f32_e32 v32, v11
	v_pk_mul_f32 v[24:25], v[10:11], v[24:25] op_sel_hi:[0,1]
	v_pk_mul_f32 v[24:25], v[2:3], v[24:25]
	v_fma_f32 v12, -v11, v32, 1.0
	v_fmac_f32_e32 v32, v12, v32
	v_div_scale_f32 v12, vcc, v16, v27, v16
	v_mul_f32_e32 v33, v12, v32
	v_fma_f32 v34, -v11, v33, v12
	v_fmac_f32_e32 v33, v34, v32
	v_fma_f32 v11, -v11, v33, v12
	v_div_scale_f32 v12, s[0:1], v26, v26, v31
	v_rcp_f32_e32 v34, v12
	v_div_fmas_f32 v11, v11, v32, v33
	v_div_fixup_f32 v27, v11, v27, v16
	v_and_b32_e32 v33, 0xffff0000, v91
	v_fma_f32 v11, -v12, v34, 1.0
	v_fmac_f32_e32 v34, v11, v34
	v_div_scale_f32 v11, vcc, v31, v26, v31
	v_mul_f32_e32 v16, v11, v34
	v_fma_f32 v32, -v12, v16, v11
	v_fmac_f32_e32 v16, v32, v34
	v_lshlrev_b32_e32 v32, 16, v91
	v_fma_f32 v11, -v12, v16, v11
	v_mul_f32_e32 v12, 0xbfb8aa3b, v32
	v_div_fmas_f32 v11, v11, v34, v16
	v_exp_f32_e32 v16, v12
	v_mul_f32_e32 v12, 0xbfb8aa3b, v33
	v_exp_f32_e32 v17, v12
	v_div_fixup_f32 v26, v11, v26, v31
	v_pk_mul_f32 v[24:25], v[24:25], v[26:27]
	v_lshlrev_b32_e32 v12, 16, v13
	v_pk_add_f32 v[16:17], v[16:17], 1.0 op_sel_hi:[1,0]
	v_and_b32_e32 v13, 0xffff0000, v13
	v_div_scale_f32 v26, s[0:1], v17, v17, v33
	v_rcp_f32_e32 v27, v26
	v_pk_mul_f32 v[10:11], v[10:11], v[12:13] op_sel_hi:[0,1]
	v_pk_mul_f32 v[10:11], v[4:5], v[10:11]
	v_fma_f32 v12, -v26, v27, 1.0
	v_fmac_f32_e32 v27, v12, v27
	v_div_scale_f32 v12, vcc, v33, v17, v33
	v_mul_f32_e32 v13, v12, v27
	v_fma_f32 v31, -v26, v13, v12
	v_fmac_f32_e32 v13, v31, v27
	v_fma_f32 v12, -v26, v13, v12
	v_div_scale_f32 v26, s[0:1], v16, v16, v32
	v_rcp_f32_e32 v31, v26
	v_div_fmas_f32 v12, v12, v27, v13
	v_div_fixup_f32 v13, v12, v17, v33
	v_fma_f32 v12, -v26, v31, 1.0
	v_fmac_f32_e32 v31, v12, v31
	v_div_scale_f32 v12, vcc, v32, v16, v32
	v_mul_f32_e32 v17, v12, v31
	v_fma_f32 v27, -v26, v17, v12
	v_fmac_f32_e32 v17, v27, v31
	v_fma_f32 v12, -v26, v17, v12
	v_div_fmas_f32 v12, v12, v31, v17
	v_div_fixup_f32 v12, v12, v16, v32
	v_pk_mul_f32 v[16:17], v[10:11], v[12:13]
	v_cvt_pk_bf16_f32 v10, v20, v21
	v_cvt_pk_bf16_f32 v11, v14, v15
	v_cvt_pk_bf16_f32 v12, v24, v25
	v_cvt_pk_bf16_f32 v13, v16, v17
	v_lshl_add_u64 v[14:15], s[36:37], 0, v[18:19]
	global_store_dwordx4 v[14:15], v[10:13], off sc1
	ds_read_b128 v[14:17], v29 offset:8448
	ds_read2_b32 v[34:35], v30 offset0:144 offset1:146
	v_or_b32_e32 v10, 16, v22
	v_mov_b32_e32 v11, v23
	v_lshlrev_b64 v[24:25], 11, v[10:11]
	v_or_b32_e32 v24, v24, v28
	v_lshl_add_u64 v[10:11], s[60:61], 0, v[24:25]
	v_lshlrev_b32_e32 v31, 16, v92
	v_and_b32_e32 v18, 0xffff0000, v92
	v_mul_f32_e32 v10, 0xbfb8aa3b, v31
	v_exp_f32_e32 v26, v10
	v_mul_f32_e32 v10, 0xbfb8aa3b, v18
	v_exp_f32_e32 v27, v10
	ds_read_b128 v[10:13], v29 offset:9504
	s_waitcnt lgkmcnt(2)
	v_lshlrev_b32_e32 v32, 16, v14
	v_and_b32_e32 v33, 0xffff0000, v14
	v_pk_add_f32 v[26:27], v[26:27], 1.0 op_sel_hi:[1,0]
	s_waitcnt lgkmcnt(1)
	v_pk_mul_f32 v[32:33], v[34:35], v[32:33] op_sel_hi:[0,1]
	v_div_scale_f32 v36, s[0:1], v27, v27, v18
	v_rcp_f32_e32 v37, v36
	v_pk_mul_f32 v[32:33], v[6:7], v[32:33]
	v_fma_f32 v14, -v36, v37, 1.0
	v_fmac_f32_e32 v37, v14, v37
	v_div_scale_f32 v14, vcc, v18, v27, v18
	v_mul_f32_e32 v38, v14, v37
	v_fma_f32 v39, -v36, v38, v14
	v_fmac_f32_e32 v38, v39, v37
	v_fma_f32 v14, -v36, v38, v14
	v_div_scale_f32 v36, s[0:1], v26, v26, v31
	v_rcp_f32_e32 v39, v36
	v_div_fmas_f32 v14, v14, v37, v38
	v_div_fixup_f32 v27, v14, v27, v18
	v_fma_f32 v14, -v36, v39, 1.0
	v_fmac_f32_e32 v39, v14, v39
	v_div_scale_f32 v14, vcc, v31, v26, v31
	v_mul_f32_e32 v18, v14, v39
	v_fma_f32 v37, -v36, v18, v14
	v_fmac_f32_e32 v18, v37, v39
	v_fma_f32 v14, -v36, v18, v14
	v_lshlrev_b32_e32 v36, 16, v93
	v_and_b32_e32 v37, 0xffff0000, v93
	v_div_fmas_f32 v14, v14, v39, v18
	v_mul_f32_e32 v18, 0xbfb8aa3b, v36
	v_mul_f32_e32 v19, 0xbfb8aa3b, v37
	v_exp_f32_e32 v18, v18
	v_exp_f32_e32 v19, v19
	v_div_fixup_f32 v26, v14, v26, v31
	v_pk_mul_f32 v[26:27], v[32:33], v[26:27]
	v_lshlrev_b32_e32 v14, 16, v15
	v_pk_add_f32 v[18:19], v[18:19], 1.0 op_sel_hi:[1,0]
	v_and_b32_e32 v15, 0xffff0000, v15
	v_div_scale_f32 v31, s[0:1], v19, v19, v37
	v_rcp_f32_e32 v32, v31
	v_pk_mul_f32 v[14:15], v[34:35], v[14:15] op_sel_hi:[0,1]
	v_pk_mul_f32 v[14:15], v[8:9], v[14:15]
	v_fma_f32 v33, -v31, v32, 1.0
	v_fmac_f32_e32 v32, v33, v32
	v_div_scale_f32 v33, vcc, v37, v19, v37
	v_mul_f32_e32 v38, v33, v32
	v_fma_f32 v39, -v31, v38, v33
	v_fmac_f32_e32 v38, v39, v32
	v_fma_f32 v31, -v31, v38, v33
	v_div_scale_f32 v33, s[0:1], v18, v18, v36
	v_rcp_f32_e32 v39, v33
	v_div_fmas_f32 v31, v31, v32, v38
	v_div_fixup_f32 v19, v31, v19, v37
	v_fma_f32 v31, -v33, v39, 1.0
	v_fmac_f32_e32 v39, v31, v39
	v_div_scale_f32 v31, vcc, v36, v18, v36
	v_mul_f32_e32 v32, v31, v39
	v_fma_f32 v37, -v33, v32, v31
	v_fmac_f32_e32 v32, v37, v39
	v_fma_f32 v31, -v33, v32, v31
	v_lshlrev_b32_e32 v37, 16, v94
	v_and_b32_e32 v20, 0xffff0000, v94
	v_div_fmas_f32 v31, v31, v39, v32
	v_mul_f32_e32 v32, 0xbfb8aa3b, v37
	v_mul_f32_e32 v33, 0xbfb8aa3b, v20
	v_exp_f32_e32 v32, v32
	v_exp_f32_e32 v33, v33
	v_div_fixup_f32 v18, v31, v18, v36
	v_pk_mul_f32 v[18:19], v[14:15], v[18:19]
	v_lshlrev_b32_e32 v14, 16, v16
	v_pk_add_f32 v[32:33], v[32:33], 1.0 op_sel_hi:[1,0]
	v_and_b32_e32 v15, 0xffff0000, v16
	v_div_scale_f32 v31, s[0:1], v33, v33, v20
	v_rcp_f32_e32 v36, v31
	v_pk_mul_f32 v[14:15], v[34:35], v[14:15] op_sel_hi:[0,1]
	v_pk_mul_f32 v[14:15], v[2:3], v[14:15]
	v_fma_f32 v16, -v31, v36, 1.0
	v_fmac_f32_e32 v36, v16, v36
	v_div_scale_f32 v16, vcc, v20, v33, v20
	v_mul_f32_e32 v38, v16, v36
	v_fma_f32 v39, -v31, v38, v16
	v_fmac_f32_e32 v38, v39, v36
	v_fma_f32 v16, -v31, v38, v16
	v_div_scale_f32 v31, s[0:1], v32, v32, v37
	v_rcp_f32_e32 v39, v31
	v_div_fmas_f32 v16, v16, v36, v38
	v_div_fixup_f32 v33, v16, v33, v20
	v_fma_f32 v16, -v31, v39, 1.0
	v_fmac_f32_e32 v39, v16, v39
	v_div_scale_f32 v16, vcc, v37, v32, v37
	v_mul_f32_e32 v20, v16, v39
	v_fma_f32 v36, -v31, v20, v16
	v_fmac_f32_e32 v20, v36, v39
	v_fma_f32 v16, -v31, v20, v16
	v_lshlrev_b32_e32 v31, 16, v95
	v_and_b32_e32 v36, 0xffff0000, v95
	v_div_fmas_f32 v16, v16, v39, v20
	v_mul_f32_e32 v20, 0xbfb8aa3b, v31
	v_mul_f32_e32 v21, 0xbfb8aa3b, v36
	v_exp_f32_e32 v20, v20
	v_exp_f32_e32 v21, v21
	v_div_fixup_f32 v32, v16, v32, v37
	v_pk_mul_f32 v[32:33], v[14:15], v[32:33]
	v_lshlrev_b32_e32 v14, 16, v17
	v_pk_add_f32 v[20:21], v[20:21], 1.0 op_sel_hi:[1,0]
	v_and_b32_e32 v15, 0xffff0000, v17
	v_div_scale_f32 v16, s[0:1], v21, v21, v36
	v_rcp_f32_e32 v37, v16
	v_pk_mul_f32 v[14:15], v[34:35], v[14:15] op_sel_hi:[0,1]
	v_pk_mul_f32 v[14:15], v[4:5], v[14:15]
	v_fma_f32 v17, -v16, v37, 1.0
	v_fmac_f32_e32 v37, v17, v37
	v_div_scale_f32 v17, vcc, v36, v21, v36
	v_mul_f32_e32 v34, v17, v37
	v_fma_f32 v38, -v16, v34, v17
	v_fmac_f32_e32 v34, v38, v37
	v_div_scale_f32 v38, s[0:1], v20, v20, v31
	v_rcp_f32_e32 v39, v38
	v_fma_f32 v16, -v16, v34, v17
	v_div_fmas_f32 v16, v16, v37, v34
	v_div_fixup_f32 v17, v16, v21, v36
	v_fma_f32 v16, -v38, v39, 1.0
	v_fmac_f32_e32 v39, v16, v39
	v_div_scale_f32 v16, vcc, v31, v20, v31
	v_mul_f32_e32 v21, v16, v39
	v_fma_f32 v34, -v38, v21, v16
	v_fmac_f32_e32 v21, v34, v39
	v_fma_f32 v16, -v38, v21, v16
	v_div_fmas_f32 v16, v16, v39, v21
	v_div_fixup_f32 v16, v16, v20, v31
	v_pk_mul_f32 v[20:21], v[14:15], v[16:17]
	v_cvt_pk_bf16_f32 v14, v26, v27
	v_cvt_pk_bf16_f32 v15, v18, v19
	v_cvt_pk_bf16_f32 v16, v32, v33
	v_cvt_pk_bf16_f32 v17, v20, v21
	v_lshl_add_u64 v[18:19], s[36:37], 0, v[24:25]
	global_store_dwordx4 v[18:19], v[14:17], off sc1
	s_waitcnt lgkmcnt(0)
	v_lshlrev_b32_e32 v24, 16, v10
	v_and_b32_e32 v25, 0xffff0000, v10
	v_or_b32_e32 v14, 18, v22
	v_mov_b32_e32 v15, v23
	v_lshlrev_b64 v[18:19], 11, v[14:15]
	v_or_b32_e32 v18, v18, v28
	v_lshl_add_u64 v[14:15], s[60:61], 0, v[18:19]
	v_mov_b32_e32 v10, v35
	v_pk_mul_f32 v[24:25], v[10:11], v[24:25] op_sel_hi:[0,1]
	v_pk_mul_f32 v[24:25], v[6:7], v[24:25]
	v_lshlrev_b32_e32 v26, 16, v96
	v_and_b32_e32 v14, 0xffff0000, v96
	v_mul_f32_e32 v20, 0xbfb8aa3b, v26
	v_mul_f32_e32 v21, 0xbfb8aa3b, v14
	v_exp_f32_e32 v20, v20
	v_exp_f32_e32 v21, v21
	s_nop 0
	v_pk_add_f32 v[20:21], v[20:21], 1.0 op_sel_hi:[1,0]
	s_nop 0
	v_div_scale_f32 v27, s[0:1], v21, v21, v14
	v_rcp_f32_e32 v31, v27
	s_nop 0
	v_fma_f32 v32, -v27, v31, 1.0
	v_fmac_f32_e32 v31, v32, v31
	v_div_scale_f32 v32, vcc, v14, v21, v14
	v_mul_f32_e32 v33, v32, v31
	v_fma_f32 v34, -v27, v33, v32
	v_fmac_f32_e32 v33, v34, v31
	v_fma_f32 v27, -v27, v33, v32
	v_div_scale_f32 v32, s[0:1], v20, v20, v26
	v_rcp_f32_e32 v34, v32
	v_div_fmas_f32 v27, v27, v31, v33
	v_div_fixup_f32 v21, v27, v21, v14
	v_fma_f32 v14, -v32, v34, 1.0
	v_fmac_f32_e32 v34, v14, v34
	v_div_scale_f32 v14, vcc, v26, v20, v26
	v_mul_f32_e32 v27, v14, v34
	v_fma_f32 v31, -v32, v27, v14
	v_fmac_f32_e32 v27, v31, v34
	v_fma_f32 v14, -v32, v27, v14
	v_lshlrev_b32_e32 v31, 16, v97
	v_and_b32_e32 v32, 0xffff0000, v97
	v_div_fmas_f32 v27, v14, v34, v27
	v_mul_f32_e32 v14, 0xbfb8aa3b, v31
	v_mul_f32_e32 v15, 0xbfb8aa3b, v32
	v_exp_f32_e32 v14, v14
	v_exp_f32_e32 v15, v15
	v_div_fixup_f32 v20, v27, v20, v26
	v_pk_mul_f32 v[20:21], v[24:25], v[20:21]
	v_lshlrev_b32_e32 v24, 16, v11
	v_pk_add_f32 v[14:15], v[14:15], 1.0 op_sel_hi:[1,0]
	v_and_b32_e32 v25, 0xffff0000, v11
	v_div_scale_f32 v26, s[0:1], v15, v15, v32
	v_rcp_f32_e32 v27, v26
	v_pk_mul_f32 v[24:25], v[10:11], v[24:25] op_sel_hi:[0,1]
	v_pk_mul_f32 v[24:25], v[8:9], v[24:25]
	v_fma_f32 v11, -v26, v27, 1.0
	v_fmac_f32_e32 v27, v11, v27
	v_div_scale_f32 v11, vcc, v32, v15, v32
	v_mul_f32_e32 v33, v11, v27
	v_fma_f32 v34, -v26, v33, v11
	v_fmac_f32_e32 v33, v34, v27
	v_fma_f32 v11, -v26, v33, v11
	v_div_scale_f32 v26, s[0:1], v14, v14, v31
	v_rcp_f32_e32 v34, v26
	v_div_fmas_f32 v11, v11, v27, v33
	v_div_fixup_f32 v15, v11, v15, v32
	v_fma_f32 v11, -v26, v34, 1.0
	v_fmac_f32_e32 v34, v11, v34
	v_div_scale_f32 v11, vcc, v31, v14, v31
	v_mul_f32_e32 v27, v11, v34
	v_fma_f32 v32, -v26, v27, v11
	v_fmac_f32_e32 v27, v32, v34
	v_fma_f32 v11, -v26, v27, v11
	v_lshlrev_b32_e32 v32, 16, v98
	v_and_b32_e32 v16, 0xffff0000, v98
	v_div_fmas_f32 v11, v11, v34, v27
	v_mul_f32_e32 v26, 0xbfb8aa3b, v32
	v_mul_f32_e32 v27, 0xbfb8aa3b, v16
	v_exp_f32_e32 v26, v26
	v_exp_f32_e32 v27, v27
	v_div_fixup_f32 v14, v11, v14, v31
	v_pk_mul_f32 v[14:15], v[24:25], v[14:15]
	v_lshlrev_b32_e32 v24, 16, v12
	v_pk_add_f32 v[26:27], v[26:27], 1.0 op_sel_hi:[1,0]
	v_and_b32_e32 v25, 0xffff0000, v12
	v_div_scale_f32 v11, s[0:1], v27, v27, v16
	v_rcp_f32_e32 v31, v11
	v_pk_mul_f32 v[24:25], v[10:11], v[24:25] op_sel_hi:[0,1]
	v_pk_mul_f32 v[24:25], v[2:3], v[24:25]
	v_fma_f32 v12, -v11, v31, 1.0
	v_fmac_f32_e32 v31, v12, v31
	v_div_scale_f32 v12, vcc, v16, v27, v16
	v_mul_f32_e32 v33, v12, v31
	v_fma_f32 v34, -v11, v33, v12
	v_fmac_f32_e32 v33, v34, v31
	v_fma_f32 v11, -v11, v33, v12
	v_div_scale_f32 v12, s[0:1], v26, v26, v32
	v_rcp_f32_e32 v34, v12
	v_div_fmas_f32 v11, v11, v31, v33
	v_div_fixup_f32 v27, v11, v27, v16
	v_and_b32_e32 v33, 0xffff0000, v99
	v_fma_f32 v11, -v12, v34, 1.0
	v_fmac_f32_e32 v34, v11, v34
	v_div_scale_f32 v11, vcc, v32, v26, v32
	v_mul_f32_e32 v16, v11, v34
	v_fma_f32 v31, -v12, v16, v11
	v_fmac_f32_e32 v16, v31, v34
	v_lshlrev_b32_e32 v31, 16, v99
	v_fma_f32 v11, -v12, v16, v11
	v_mul_f32_e32 v12, 0xbfb8aa3b, v31
	v_div_fmas_f32 v11, v11, v34, v16
	v_exp_f32_e32 v16, v12
	v_mul_f32_e32 v12, 0xbfb8aa3b, v33
	v_exp_f32_e32 v17, v12
	v_div_fixup_f32 v26, v11, v26, v32
	v_pk_mul_f32 v[24:25], v[24:25], v[26:27]
	v_lshlrev_b32_e32 v12, 16, v13
	v_pk_add_f32 v[16:17], v[16:17], 1.0 op_sel_hi:[1,0]
	v_and_b32_e32 v13, 0xffff0000, v13
	v_div_scale_f32 v26, s[0:1], v17, v17, v33
	v_rcp_f32_e32 v27, v26
	v_pk_mul_f32 v[10:11], v[10:11], v[12:13] op_sel_hi:[0,1]
	v_pk_mul_f32 v[10:11], v[4:5], v[10:11]
	v_fma_f32 v12, -v26, v27, 1.0
	v_fmac_f32_e32 v27, v12, v27
	v_div_scale_f32 v12, vcc, v33, v17, v33
	v_mul_f32_e32 v13, v12, v27
	v_fma_f32 v32, -v26, v13, v12
	v_fmac_f32_e32 v13, v32, v27
	v_fma_f32 v12, -v26, v13, v12
	v_div_scale_f32 v26, s[0:1], v16, v16, v31
	v_rcp_f32_e32 v32, v26
	v_div_fmas_f32 v12, v12, v27, v13
	v_div_fixup_f32 v13, v12, v17, v33
	v_fma_f32 v12, -v26, v32, 1.0
	v_fmac_f32_e32 v32, v12, v32
	v_div_scale_f32 v12, vcc, v31, v16, v31
	v_mul_f32_e32 v17, v12, v32
	v_fma_f32 v27, -v26, v17, v12
	v_fmac_f32_e32 v17, v27, v32
	v_fma_f32 v12, -v26, v17, v12
	v_div_fmas_f32 v12, v12, v32, v17
	v_div_fixup_f32 v12, v12, v16, v31
	v_pk_mul_f32 v[16:17], v[10:11], v[12:13]
	v_cvt_pk_bf16_f32 v10, v20, v21
	v_cvt_pk_bf16_f32 v11, v14, v15
	v_cvt_pk_bf16_f32 v12, v24, v25
	v_cvt_pk_bf16_f32 v13, v16, v17
	v_lshl_add_u64 v[14:15], s[36:37], 0, v[18:19]
	global_store_dwordx4 v[14:15], v[10:13], off sc1
	ds_read_b128 v[14:17], v29 offset:10560
	s_waitcnt lgkmcnt(0)
	v_lshlrev_b32_e32 v34, 16, v14
	v_or_b32_e32 v10, 20, v22
	v_mov_b32_e32 v11, v23
	v_lshlrev_b64 v[26:27], 11, v[10:11]
	v_or_b32_e32 v26, v26, v28
	v_lshl_add_u64 v[10:11], s[60:61], 0, v[26:27]
	v_and_b32_e32 v35, 0xffff0000, v14
	v_lshlrev_b32_e32 v31, 16, v100
	v_and_b32_e32 v18, 0xffff0000, v100
	v_mul_f32_e32 v10, 0xbfb8aa3b, v31
	v_exp_f32_e32 v32, v10
	v_mul_f32_e32 v10, 0xbfb8aa3b, v18
	v_exp_f32_e32 v33, v10
	ds_read2_b32 v[24:25], v30 offset0:148 offset1:150
	ds_read_b128 v[10:13], v29 offset:11616
	v_pk_add_f32 v[32:33], v[32:33], 1.0 op_sel_hi:[1,0]
	s_nop 0
	v_div_scale_f32 v36, s[0:1], v33, v33, v18
	v_rcp_f32_e32 v37, v36
	s_waitcnt lgkmcnt(1)
	v_pk_mul_f32 v[34:35], v[24:25], v[34:35] op_sel_hi:[0,1]
	v_pk_mul_f32 v[34:35], v[6:7], v[34:35]
	v_fma_f32 v14, -v36, v37, 1.0
	v_fmac_f32_e32 v37, v14, v37
	v_div_scale_f32 v14, vcc, v18, v33, v18
	v_mul_f32_e32 v38, v14, v37
	v_fma_f32 v39, -v36, v38, v14
	v_fmac_f32_e32 v38, v39, v37
	v_fma_f32 v14, -v36, v38, v14
	v_div_scale_f32 v36, s[0:1], v32, v32, v31
	v_rcp_f32_e32 v39, v36
	v_div_fmas_f32 v14, v14, v37, v38
	v_div_fixup_f32 v33, v14, v33, v18
	v_fma_f32 v14, -v36, v39, 1.0
	v_fmac_f32_e32 v39, v14, v39
	v_div_scale_f32 v14, vcc, v31, v32, v31
	v_mul_f32_e32 v18, v14, v39
	v_fma_f32 v37, -v36, v18, v14
	v_fmac_f32_e32 v18, v37, v39
	v_fma_f32 v14, -v36, v18, v14
	v_lshlrev_b32_e32 v36, 16, v101
	v_and_b32_e32 v37, 0xffff0000, v101
	v_div_fmas_f32 v14, v14, v39, v18
	v_mul_f32_e32 v18, 0xbfb8aa3b, v36
	v_mul_f32_e32 v19, 0xbfb8aa3b, v37
	v_exp_f32_e32 v18, v18
	v_exp_f32_e32 v19, v19
	v_div_fixup_f32 v32, v14, v32, v31
	v_pk_mul_f32 v[32:33], v[34:35], v[32:33]
	v_lshlrev_b32_e32 v14, 16, v15
	v_pk_add_f32 v[18:19], v[18:19], 1.0 op_sel_hi:[1,0]
	v_and_b32_e32 v15, 0xffff0000, v15
	v_div_scale_f32 v31, s[0:1], v19, v19, v37
	v_rcp_f32_e32 v34, v31
	v_pk_mul_f32 v[14:15], v[24:25], v[14:15] op_sel_hi:[0,1]
	v_pk_mul_f32 v[14:15], v[8:9], v[14:15]
	v_fma_f32 v35, -v31, v34, 1.0
	v_fmac_f32_e32 v34, v35, v34
	v_div_scale_f32 v35, vcc, v37, v19, v37
	v_mul_f32_e32 v38, v35, v34
	v_fma_f32 v39, -v31, v38, v35
	v_fmac_f32_e32 v38, v39, v34
	v_fma_f32 v31, -v31, v38, v35
	v_div_scale_f32 v35, s[0:1], v18, v18, v36
	v_rcp_f32_e32 v39, v35
	v_div_fmas_f32 v31, v31, v34, v38
	v_div_fixup_f32 v19, v31, v19, v37
	v_fma_f32 v31, -v35, v39, 1.0
	v_fmac_f32_e32 v39, v31, v39
	v_div_scale_f32 v31, vcc, v36, v18, v36
	v_mul_f32_e32 v34, v31, v39
	v_fma_f32 v37, -v35, v34, v31
	v_fmac_f32_e32 v34, v37, v39
	v_fma_f32 v31, -v35, v34, v31
	v_lshlrev_b32_e32 v37, 16, v102
	v_and_b32_e32 v20, 0xffff0000, v102
	v_div_fmas_f32 v31, v31, v39, v34
	v_mul_f32_e32 v34, 0xbfb8aa3b, v37
	v_mul_f32_e32 v35, 0xbfb8aa3b, v20
	v_exp_f32_e32 v34, v34
	v_exp_f32_e32 v35, v35
	v_div_fixup_f32 v18, v31, v18, v36
	v_pk_mul_f32 v[18:19], v[14:15], v[18:19]
	v_lshlrev_b32_e32 v14, 16, v16
	v_pk_add_f32 v[34:35], v[34:35], 1.0 op_sel_hi:[1,0]
	v_and_b32_e32 v15, 0xffff0000, v16
	v_div_scale_f32 v31, s[0:1], v35, v35, v20
	v_rcp_f32_e32 v36, v31
	v_pk_mul_f32 v[14:15], v[24:25], v[14:15] op_sel_hi:[0,1]
	v_pk_mul_f32 v[14:15], v[2:3], v[14:15]
	v_fma_f32 v16, -v31, v36, 1.0
	v_fmac_f32_e32 v36, v16, v36
	v_div_scale_f32 v16, vcc, v20, v35, v20
	v_mul_f32_e32 v38, v16, v36
	v_fma_f32 v39, -v31, v38, v16
	v_fmac_f32_e32 v38, v39, v36
	v_fma_f32 v16, -v31, v38, v16
	v_div_scale_f32 v31, s[0:1], v34, v34, v37
	v_rcp_f32_e32 v39, v31
	v_div_fmas_f32 v16, v16, v36, v38
	v_div_fixup_f32 v35, v16, v35, v20
	v_fma_f32 v16, -v31, v39, 1.0
	v_fmac_f32_e32 v39, v16, v39
	v_div_scale_f32 v16, vcc, v37, v34, v37
	v_mul_f32_e32 v20, v16, v39
	v_fma_f32 v36, -v31, v20, v16
	v_fmac_f32_e32 v20, v36, v39
	v_fma_f32 v16, -v31, v20, v16
	v_lshlrev_b32_e32 v31, 16, v103
	v_and_b32_e32 v36, 0xffff0000, v103
	v_div_fmas_f32 v16, v16, v39, v20
	v_mul_f32_e32 v20, 0xbfb8aa3b, v31
	v_mul_f32_e32 v21, 0xbfb8aa3b, v36
	v_exp_f32_e32 v20, v20
	v_exp_f32_e32 v21, v21
	v_div_fixup_f32 v34, v16, v34, v37
	v_pk_mul_f32 v[34:35], v[14:15], v[34:35]
	v_lshlrev_b32_e32 v14, 16, v17
	v_pk_add_f32 v[20:21], v[20:21], 1.0 op_sel_hi:[1,0]
	v_and_b32_e32 v15, 0xffff0000, v17
	v_div_scale_f32 v16, s[0:1], v21, v21, v36
	v_rcp_f32_e32 v37, v16
	v_pk_mul_f32 v[14:15], v[24:25], v[14:15] op_sel_hi:[0,1]
	v_pk_mul_f32 v[14:15], v[4:5], v[14:15]
	v_fma_f32 v17, -v16, v37, 1.0
	v_fmac_f32_e32 v37, v17, v37
	v_div_scale_f32 v17, vcc, v36, v21, v36
	v_mul_f32_e32 v24, v17, v37
	v_fma_f32 v38, -v16, v24, v17
	v_fmac_f32_e32 v24, v38, v37
	v_div_scale_f32 v38, s[0:1], v20, v20, v31
	v_rcp_f32_e32 v39, v38
	v_fma_f32 v16, -v16, v24, v17
	v_div_fmas_f32 v16, v16, v37, v24
	v_div_fixup_f32 v17, v16, v21, v36
	v_fma_f32 v16, -v38, v39, 1.0
	v_fmac_f32_e32 v39, v16, v39
	v_div_scale_f32 v16, vcc, v31, v20, v31
	v_mul_f32_e32 v21, v16, v39
	v_fma_f32 v24, -v38, v21, v16
	v_fmac_f32_e32 v21, v24, v39
	v_fma_f32 v16, -v38, v21, v16
	v_div_fmas_f32 v16, v16, v39, v21
	v_div_fixup_f32 v16, v16, v20, v31
	v_pk_mul_f32 v[20:21], v[14:15], v[16:17]
	v_cvt_pk_bf16_f32 v14, v32, v33
	v_cvt_pk_bf16_f32 v15, v18, v19
	v_cvt_pk_bf16_f32 v16, v34, v35
	v_cvt_pk_bf16_f32 v17, v20, v21
	v_lshl_add_u64 v[18:19], s[36:37], 0, v[26:27]
	global_store_dwordx4 v[18:19], v[14:17], off sc1
	s_waitcnt lgkmcnt(0)
	v_lshlrev_b32_e32 v26, 16, v10
	v_and_b32_e32 v27, 0xffff0000, v10
	v_or_b32_e32 v14, 22, v22
	v_mov_b32_e32 v15, v23
	v_lshlrev_b64 v[18:19], 11, v[14:15]
	v_or_b32_e32 v18, v18, v28
	v_lshl_add_u64 v[14:15], s[60:61], 0, v[18:19]
	v_mov_b32_e32 v10, v25
	v_pk_mul_f32 v[24:25], v[10:11], v[26:27] op_sel_hi:[0,1]
	v_pk_mul_f32 v[24:25], v[6:7], v[24:25]
	v_lshlrev_b32_e32 v31, 16, v104
	v_and_b32_e32 v14, 0xffff0000, v104
	v_mul_f32_e32 v20, 0xbfb8aa3b, v31
	v_mul_f32_e32 v21, 0xbfb8aa3b, v14
	v_exp_f32_e32 v20, v20
	v_exp_f32_e32 v21, v21
	s_nop 0
	v_pk_add_f32 v[20:21], v[20:21], 1.0 op_sel_hi:[1,0]
	s_nop 0
	v_div_scale_f32 v32, s[0:1], v21, v21, v14
	v_rcp_f32_e32 v33, v32
	s_nop 0
	v_fma_f32 v26, -v32, v33, 1.0
	v_fmac_f32_e32 v33, v26, v33
	v_div_scale_f32 v26, vcc, v14, v21, v14
	v_mul_f32_e32 v27, v26, v33
	v_fma_f32 v34, -v32, v27, v26
	v_fmac_f32_e32 v27, v34, v33
	v_fma_f32 v26, -v32, v27, v26
	v_div_scale_f32 v32, s[0:1], v20, v20, v31
	v_rcp_f32_e32 v34, v32
	v_div_fmas_f32 v26, v26, v33, v27
	v_div_fixup_f32 v21, v26, v21, v14
	v_fma_f32 v14, -v32, v34, 1.0
	v_fmac_f32_e32 v34, v14, v34
	v_div_scale_f32 v14, vcc, v31, v20, v31
	v_mul_f32_e32 v26, v14, v34
	v_fma_f32 v27, -v32, v26, v14
	v_fmac_f32_e32 v26, v27, v34
	v_fma_f32 v14, -v32, v26, v14
	v_lshlrev_b32_e32 v32, 16, v105
	v_and_b32_e32 v27, 0xffff0000, v105
	v_div_fmas_f32 v26, v14, v34, v26
	v_mul_f32_e32 v14, 0xbfb8aa3b, v32
	v_mul_f32_e32 v15, 0xbfb8aa3b, v27
	v_exp_f32_e32 v14, v14
	v_exp_f32_e32 v15, v15
	v_div_fixup_f32 v20, v26, v20, v31
	v_pk_mul_f32 v[20:21], v[24:25], v[20:21]
	v_lshlrev_b32_e32 v24, 16, v11
	v_pk_add_f32 v[14:15], v[14:15], 1.0 op_sel_hi:[1,0]
	v_and_b32_e32 v25, 0xffff0000, v11
	v_div_scale_f32 v26, s[0:1], v15, v15, v27
	v_rcp_f32_e32 v31, v26
	v_pk_mul_f32 v[24:25], v[10:11], v[24:25] op_sel_hi:[0,1]
	v_pk_mul_f32 v[24:25], v[8:9], v[24:25]
	v_fma_f32 v11, -v26, v31, 1.0
	v_fmac_f32_e32 v31, v11, v31
	v_div_scale_f32 v11, vcc, v27, v15, v27
	v_mul_f32_e32 v33, v11, v31
	v_fma_f32 v34, -v26, v33, v11
	v_fmac_f32_e32 v33, v34, v31
	v_fma_f32 v11, -v26, v33, v11
	v_div_scale_f32 v26, s[0:1], v14, v14, v32
	v_rcp_f32_e32 v34, v26
	v_div_fmas_f32 v11, v11, v31, v33
	v_div_fixup_f32 v15, v11, v15, v27
	v_fma_f32 v11, -v26, v34, 1.0
	v_fmac_f32_e32 v34, v11, v34
	v_div_scale_f32 v11, vcc, v32, v14, v32
	v_mul_f32_e32 v27, v11, v34
	v_fma_f32 v31, -v26, v27, v11
	v_fmac_f32_e32 v27, v31, v34
	v_fma_f32 v11, -v26, v27, v11
	v_lshlrev_b32_e32 v31, 16, v106
	v_and_b32_e32 v16, 0xffff0000, v106
	v_div_fmas_f32 v11, v11, v34, v27
	v_mul_f32_e32 v26, 0xbfb8aa3b, v31
	v_mul_f32_e32 v27, 0xbfb8aa3b, v16
	v_exp_f32_e32 v26, v26
	v_exp_f32_e32 v27, v27
	v_div_fixup_f32 v14, v11, v14, v32
	v_pk_mul_f32 v[14:15], v[24:25], v[14:15]
	v_lshlrev_b32_e32 v24, 16, v12
	v_pk_add_f32 v[26:27], v[26:27], 1.0 op_sel_hi:[1,0]
	v_and_b32_e32 v25, 0xffff0000, v12
	v_div_scale_f32 v11, s[0:1], v27, v27, v16
	v_rcp_f32_e32 v32, v11
	v_pk_mul_f32 v[24:25], v[10:11], v[24:25] op_sel_hi:[0,1]
	v_pk_mul_f32 v[24:25], v[2:3], v[24:25]
	v_fma_f32 v12, -v11, v32, 1.0
	v_fmac_f32_e32 v32, v12, v32
	v_div_scale_f32 v12, vcc, v16, v27, v16
	v_mul_f32_e32 v33, v12, v32
	v_fma_f32 v34, -v11, v33, v12
	v_fmac_f32_e32 v33, v34, v32
	v_fma_f32 v11, -v11, v33, v12
	v_div_scale_f32 v12, s[0:1], v26, v26, v31
	v_rcp_f32_e32 v34, v12
	v_div_fmas_f32 v11, v11, v32, v33
	v_div_fixup_f32 v27, v11, v27, v16
	v_and_b32_e32 v33, 0xffff0000, v107
	v_fma_f32 v11, -v12, v34, 1.0
	v_fmac_f32_e32 v34, v11, v34
	v_div_scale_f32 v11, vcc, v31, v26, v31
	v_mul_f32_e32 v16, v11, v34
	v_fma_f32 v32, -v12, v16, v11
	v_fmac_f32_e32 v16, v32, v34
	v_lshlrev_b32_e32 v32, 16, v107
	v_fma_f32 v11, -v12, v16, v11
	v_mul_f32_e32 v12, 0xbfb8aa3b, v32
	v_div_fmas_f32 v11, v11, v34, v16
	v_exp_f32_e32 v16, v12
	v_mul_f32_e32 v12, 0xbfb8aa3b, v33
	v_exp_f32_e32 v17, v12
	v_div_fixup_f32 v26, v11, v26, v31
	v_pk_mul_f32 v[24:25], v[24:25], v[26:27]
	v_lshlrev_b32_e32 v12, 16, v13
	v_pk_add_f32 v[16:17], v[16:17], 1.0 op_sel_hi:[1,0]
	v_and_b32_e32 v13, 0xffff0000, v13
	v_div_scale_f32 v26, s[0:1], v17, v17, v33
	v_rcp_f32_e32 v27, v26
	v_pk_mul_f32 v[10:11], v[10:11], v[12:13] op_sel_hi:[0,1]
	v_pk_mul_f32 v[10:11], v[4:5], v[10:11]
	v_fma_f32 v12, -v26, v27, 1.0
	v_fmac_f32_e32 v27, v12, v27
	v_div_scale_f32 v12, vcc, v33, v17, v33
	v_mul_f32_e32 v13, v12, v27
	v_fma_f32 v31, -v26, v13, v12
	v_fmac_f32_e32 v13, v31, v27
	v_fma_f32 v12, -v26, v13, v12
	v_div_scale_f32 v26, s[0:1], v16, v16, v32
	v_rcp_f32_e32 v31, v26
	v_div_fmas_f32 v12, v12, v27, v13
	v_div_fixup_f32 v13, v12, v17, v33
	v_fma_f32 v12, -v26, v31, 1.0
	v_fmac_f32_e32 v31, v12, v31
	v_div_scale_f32 v12, vcc, v32, v16, v32
	v_mul_f32_e32 v17, v12, v31
	v_fma_f32 v27, -v26, v17, v12
	v_fmac_f32_e32 v17, v27, v31
	v_fma_f32 v12, -v26, v17, v12
	v_div_fmas_f32 v12, v12, v31, v17
	v_div_fixup_f32 v12, v12, v16, v32
	v_pk_mul_f32 v[16:17], v[10:11], v[12:13]
	v_cvt_pk_bf16_f32 v10, v20, v21
	v_cvt_pk_bf16_f32 v11, v14, v15
	v_cvt_pk_bf16_f32 v12, v24, v25
	v_cvt_pk_bf16_f32 v13, v16, v17
	v_lshl_add_u64 v[14:15], s[36:37], 0, v[18:19]
	global_store_dwordx4 v[14:15], v[10:13], off sc1
	ds_read_b128 v[14:17], v29 offset:12672
	s_waitcnt lgkmcnt(0)
	v_lshlrev_b32_e32 v34, 16, v14
	v_or_b32_e32 v10, 24, v22
	v_mov_b32_e32 v11, v23
	v_lshlrev_b64 v[26:27], 11, v[10:11]
	v_or_b32_e32 v26, v26, v28
	v_lshl_add_u64 v[10:11], s[60:61], 0, v[26:27]
	v_and_b32_e32 v35, 0xffff0000, v14
	v_lshlrev_b32_e32 v31, 16, v108
	v_and_b32_e32 v18, 0xffff0000, v108
	v_mul_f32_e32 v10, 0xbfb8aa3b, v31
	v_exp_f32_e32 v32, v10
	v_mul_f32_e32 v10, 0xbfb8aa3b, v18
	v_exp_f32_e32 v33, v10
	ds_read2_b32 v[24:25], v30 offset0:152 offset1:154
	ds_read_b128 v[10:13], v29 offset:13728
	v_pk_add_f32 v[32:33], v[32:33], 1.0 op_sel_hi:[1,0]
	s_nop 0
	v_div_scale_f32 v36, s[0:1], v33, v33, v18
	v_rcp_f32_e32 v37, v36
	s_waitcnt lgkmcnt(1)
	v_pk_mul_f32 v[34:35], v[24:25], v[34:35] op_sel_hi:[0,1]
	v_pk_mul_f32 v[34:35], v[6:7], v[34:35]
	v_fma_f32 v14, -v36, v37, 1.0
	v_fmac_f32_e32 v37, v14, v37
	v_div_scale_f32 v14, vcc, v18, v33, v18
	v_mul_f32_e32 v38, v14, v37
	v_fma_f32 v39, -v36, v38, v14
	v_fmac_f32_e32 v38, v39, v37
	v_fma_f32 v14, -v36, v38, v14
	v_div_scale_f32 v36, s[0:1], v32, v32, v31
	v_rcp_f32_e32 v39, v36
	v_div_fmas_f32 v14, v14, v37, v38
	v_div_fixup_f32 v33, v14, v33, v18
	v_fma_f32 v14, -v36, v39, 1.0
	v_fmac_f32_e32 v39, v14, v39
	v_div_scale_f32 v14, vcc, v31, v32, v31
	v_mul_f32_e32 v18, v14, v39
	v_fma_f32 v37, -v36, v18, v14
	v_fmac_f32_e32 v18, v37, v39
	v_fma_f32 v14, -v36, v18, v14
	v_lshlrev_b32_e32 v36, 16, v109
	v_and_b32_e32 v37, 0xffff0000, v109
	v_div_fmas_f32 v14, v14, v39, v18
	v_mul_f32_e32 v18, 0xbfb8aa3b, v36
	v_mul_f32_e32 v19, 0xbfb8aa3b, v37
	v_exp_f32_e32 v18, v18
	v_exp_f32_e32 v19, v19
	v_div_fixup_f32 v32, v14, v32, v31
	v_pk_mul_f32 v[32:33], v[34:35], v[32:33]
	v_lshlrev_b32_e32 v14, 16, v15
	v_pk_add_f32 v[18:19], v[18:19], 1.0 op_sel_hi:[1,0]
	v_and_b32_e32 v15, 0xffff0000, v15
	v_div_scale_f32 v31, s[0:1], v19, v19, v37
	v_rcp_f32_e32 v34, v31
	v_pk_mul_f32 v[14:15], v[24:25], v[14:15] op_sel_hi:[0,1]
	v_pk_mul_f32 v[14:15], v[8:9], v[14:15]
	v_fma_f32 v35, -v31, v34, 1.0
	v_fmac_f32_e32 v34, v35, v34
	v_div_scale_f32 v35, vcc, v37, v19, v37
	v_mul_f32_e32 v38, v35, v34
	v_fma_f32 v39, -v31, v38, v35
	v_fmac_f32_e32 v38, v39, v34
	v_fma_f32 v31, -v31, v38, v35
	v_div_scale_f32 v35, s[0:1], v18, v18, v36
	v_rcp_f32_e32 v39, v35
	v_div_fmas_f32 v31, v31, v34, v38
	v_div_fixup_f32 v19, v31, v19, v37
	v_fma_f32 v31, -v35, v39, 1.0
	v_fmac_f32_e32 v39, v31, v39
	v_div_scale_f32 v31, vcc, v36, v18, v36
	v_mul_f32_e32 v34, v31, v39
	v_fma_f32 v37, -v35, v34, v31
	v_fmac_f32_e32 v34, v37, v39
	v_fma_f32 v31, -v35, v34, v31
	v_lshlrev_b32_e32 v37, 16, v110
	v_and_b32_e32 v20, 0xffff0000, v110
	v_div_fmas_f32 v31, v31, v39, v34
	v_mul_f32_e32 v34, 0xbfb8aa3b, v37
	v_mul_f32_e32 v35, 0xbfb8aa3b, v20
	v_exp_f32_e32 v34, v34
	v_exp_f32_e32 v35, v35
	v_div_fixup_f32 v18, v31, v18, v36
	v_pk_mul_f32 v[18:19], v[14:15], v[18:19]
	v_lshlrev_b32_e32 v14, 16, v16
	v_pk_add_f32 v[34:35], v[34:35], 1.0 op_sel_hi:[1,0]
	v_and_b32_e32 v15, 0xffff0000, v16
	v_div_scale_f32 v31, s[0:1], v35, v35, v20
	v_rcp_f32_e32 v36, v31
	v_pk_mul_f32 v[14:15], v[24:25], v[14:15] op_sel_hi:[0,1]
	v_pk_mul_f32 v[14:15], v[2:3], v[14:15]
	v_fma_f32 v16, -v31, v36, 1.0
	v_fmac_f32_e32 v36, v16, v36
	v_div_scale_f32 v16, vcc, v20, v35, v20
	v_mul_f32_e32 v38, v16, v36
	v_fma_f32 v39, -v31, v38, v16
	v_fmac_f32_e32 v38, v39, v36
	v_fma_f32 v16, -v31, v38, v16
	v_div_scale_f32 v31, s[0:1], v34, v34, v37
	v_rcp_f32_e32 v39, v31
	v_div_fmas_f32 v16, v16, v36, v38
	v_div_fixup_f32 v35, v16, v35, v20
	v_fma_f32 v16, -v31, v39, 1.0
	v_fmac_f32_e32 v39, v16, v39
	v_div_scale_f32 v16, vcc, v37, v34, v37
	v_mul_f32_e32 v20, v16, v39
	v_fma_f32 v36, -v31, v20, v16
	v_fmac_f32_e32 v20, v36, v39
	v_fma_f32 v16, -v31, v20, v16
	v_lshlrev_b32_e32 v31, 16, v111
	v_and_b32_e32 v36, 0xffff0000, v111
	v_div_fmas_f32 v16, v16, v39, v20
	v_mul_f32_e32 v20, 0xbfb8aa3b, v31
	v_mul_f32_e32 v21, 0xbfb8aa3b, v36
	v_exp_f32_e32 v20, v20
	v_exp_f32_e32 v21, v21
	v_div_fixup_f32 v34, v16, v34, v37
	v_pk_mul_f32 v[34:35], v[14:15], v[34:35]
	v_lshlrev_b32_e32 v14, 16, v17
	v_pk_add_f32 v[20:21], v[20:21], 1.0 op_sel_hi:[1,0]
	v_and_b32_e32 v15, 0xffff0000, v17
	v_div_scale_f32 v16, s[0:1], v21, v21, v36
	v_rcp_f32_e32 v37, v16
	v_pk_mul_f32 v[14:15], v[24:25], v[14:15] op_sel_hi:[0,1]
	v_pk_mul_f32 v[14:15], v[4:5], v[14:15]
	v_fma_f32 v17, -v16, v37, 1.0
	v_fmac_f32_e32 v37, v17, v37
	v_div_scale_f32 v17, vcc, v36, v21, v36
	v_mul_f32_e32 v24, v17, v37
	v_fma_f32 v38, -v16, v24, v17
	v_fmac_f32_e32 v24, v38, v37
	v_div_scale_f32 v38, s[0:1], v20, v20, v31
	v_rcp_f32_e32 v39, v38
	v_fma_f32 v16, -v16, v24, v17
	v_div_fmas_f32 v16, v16, v37, v24
	v_div_fixup_f32 v17, v16, v21, v36
	v_fma_f32 v16, -v38, v39, 1.0
	v_fmac_f32_e32 v39, v16, v39
	v_div_scale_f32 v16, vcc, v31, v20, v31
	v_mul_f32_e32 v21, v16, v39
	v_fma_f32 v24, -v38, v21, v16
	v_fmac_f32_e32 v21, v24, v39
	v_fma_f32 v16, -v38, v21, v16
	v_div_fmas_f32 v16, v16, v39, v21
	v_div_fixup_f32 v16, v16, v20, v31
	v_pk_mul_f32 v[20:21], v[14:15], v[16:17]
	v_cvt_pk_bf16_f32 v14, v32, v33
	v_cvt_pk_bf16_f32 v15, v18, v19
	v_cvt_pk_bf16_f32 v16, v34, v35
	v_cvt_pk_bf16_f32 v17, v20, v21
	v_lshl_add_u64 v[18:19], s[36:37], 0, v[26:27]
	global_store_dwordx4 v[18:19], v[14:17], off sc1
	s_waitcnt lgkmcnt(0)
	v_lshlrev_b32_e32 v26, 16, v10
	v_and_b32_e32 v27, 0xffff0000, v10
	v_or_b32_e32 v14, 26, v22
	v_mov_b32_e32 v15, v23
	v_lshlrev_b64 v[18:19], 11, v[14:15]
	v_or_b32_e32 v18, v18, v28
	v_lshl_add_u64 v[14:15], s[60:61], 0, v[18:19]
	v_mov_b32_e32 v10, v25
	v_pk_mul_f32 v[24:25], v[10:11], v[26:27] op_sel_hi:[0,1]
	v_pk_mul_f32 v[24:25], v[6:7], v[24:25]
	v_lshlrev_b32_e32 v31, 16, v112
	v_and_b32_e32 v14, 0xffff0000, v112
	v_mul_f32_e32 v20, 0xbfb8aa3b, v31
	v_mul_f32_e32 v21, 0xbfb8aa3b, v14
	v_exp_f32_e32 v20, v20
	v_exp_f32_e32 v21, v21
	s_nop 0
	v_pk_add_f32 v[20:21], v[20:21], 1.0 op_sel_hi:[1,0]
	s_nop 0
	v_div_scale_f32 v32, s[0:1], v21, v21, v14
	v_rcp_f32_e32 v33, v32
	s_nop 0
	v_fma_f32 v26, -v32, v33, 1.0
	v_fmac_f32_e32 v33, v26, v33
	v_div_scale_f32 v26, vcc, v14, v21, v14
	v_mul_f32_e32 v27, v26, v33
	v_fma_f32 v34, -v32, v27, v26
	v_fmac_f32_e32 v27, v34, v33
	v_fma_f32 v26, -v32, v27, v26
	v_div_scale_f32 v32, s[0:1], v20, v20, v31
	v_rcp_f32_e32 v34, v32
	v_div_fmas_f32 v26, v26, v33, v27
	v_div_fixup_f32 v21, v26, v21, v14
	v_fma_f32 v14, -v32, v34, 1.0
	v_fmac_f32_e32 v34, v14, v34
	v_div_scale_f32 v14, vcc, v31, v20, v31
	v_mul_f32_e32 v26, v14, v34
	v_fma_f32 v27, -v32, v26, v14
	v_fmac_f32_e32 v26, v27, v34
	v_fma_f32 v14, -v32, v26, v14
	v_lshlrev_b32_e32 v32, 16, v113
	v_and_b32_e32 v27, 0xffff0000, v113
	v_div_fmas_f32 v26, v14, v34, v26
	v_mul_f32_e32 v14, 0xbfb8aa3b, v32
	v_mul_f32_e32 v15, 0xbfb8aa3b, v27
	v_exp_f32_e32 v14, v14
	v_exp_f32_e32 v15, v15
	v_div_fixup_f32 v20, v26, v20, v31
	v_pk_mul_f32 v[20:21], v[24:25], v[20:21]
	v_lshlrev_b32_e32 v24, 16, v11
	v_pk_add_f32 v[14:15], v[14:15], 1.0 op_sel_hi:[1,0]
	v_and_b32_e32 v25, 0xffff0000, v11
	v_div_scale_f32 v26, s[0:1], v15, v15, v27
	v_rcp_f32_e32 v31, v26
	v_pk_mul_f32 v[24:25], v[10:11], v[24:25] op_sel_hi:[0,1]
	v_pk_mul_f32 v[24:25], v[8:9], v[24:25]
	v_fma_f32 v11, -v26, v31, 1.0
	v_fmac_f32_e32 v31, v11, v31
	v_div_scale_f32 v11, vcc, v27, v15, v27
	v_mul_f32_e32 v33, v11, v31
	v_fma_f32 v34, -v26, v33, v11
	v_fmac_f32_e32 v33, v34, v31
	v_fma_f32 v11, -v26, v33, v11
	v_div_scale_f32 v26, s[0:1], v14, v14, v32
	v_rcp_f32_e32 v34, v26
	v_div_fmas_f32 v11, v11, v31, v33
	v_div_fixup_f32 v15, v11, v15, v27
	v_fma_f32 v11, -v26, v34, 1.0
	v_fmac_f32_e32 v34, v11, v34
	v_div_scale_f32 v11, vcc, v32, v14, v32
	v_mul_f32_e32 v27, v11, v34
	v_fma_f32 v31, -v26, v27, v11
	v_fmac_f32_e32 v27, v31, v34
	v_fma_f32 v11, -v26, v27, v11
	v_lshlrev_b32_e32 v31, 16, v114
	v_and_b32_e32 v16, 0xffff0000, v114
	v_div_fmas_f32 v11, v11, v34, v27
	v_mul_f32_e32 v26, 0xbfb8aa3b, v31
	v_mul_f32_e32 v27, 0xbfb8aa3b, v16
	v_exp_f32_e32 v26, v26
	v_exp_f32_e32 v27, v27
	v_div_fixup_f32 v14, v11, v14, v32
	v_pk_mul_f32 v[14:15], v[24:25], v[14:15]
	v_lshlrev_b32_e32 v24, 16, v12
	v_pk_add_f32 v[26:27], v[26:27], 1.0 op_sel_hi:[1,0]
	v_and_b32_e32 v25, 0xffff0000, v12
	v_div_scale_f32 v11, s[0:1], v27, v27, v16
	v_rcp_f32_e32 v32, v11
	v_pk_mul_f32 v[24:25], v[10:11], v[24:25] op_sel_hi:[0,1]
	v_pk_mul_f32 v[24:25], v[2:3], v[24:25]
	v_fma_f32 v12, -v11, v32, 1.0
	v_fmac_f32_e32 v32, v12, v32
	v_div_scale_f32 v12, vcc, v16, v27, v16
	v_mul_f32_e32 v33, v12, v32
	v_fma_f32 v34, -v11, v33, v12
	v_fmac_f32_e32 v33, v34, v32
	v_fma_f32 v11, -v11, v33, v12
	v_div_scale_f32 v12, s[0:1], v26, v26, v31
	v_rcp_f32_e32 v34, v12
	v_div_fmas_f32 v11, v11, v32, v33
	v_div_fixup_f32 v27, v11, v27, v16
	v_and_b32_e32 v33, 0xffff0000, v115
	v_fma_f32 v11, -v12, v34, 1.0
	v_fmac_f32_e32 v34, v11, v34
	v_div_scale_f32 v11, vcc, v31, v26, v31
	v_mul_f32_e32 v16, v11, v34
	v_fma_f32 v32, -v12, v16, v11
	v_fmac_f32_e32 v16, v32, v34
	v_lshlrev_b32_e32 v32, 16, v115
	v_fma_f32 v11, -v12, v16, v11
	v_mul_f32_e32 v12, 0xbfb8aa3b, v32
	v_div_fmas_f32 v11, v11, v34, v16
	v_exp_f32_e32 v16, v12
	v_mul_f32_e32 v12, 0xbfb8aa3b, v33
	v_exp_f32_e32 v17, v12
	v_div_fixup_f32 v26, v11, v26, v31
	v_pk_mul_f32 v[24:25], v[24:25], v[26:27]
	v_lshlrev_b32_e32 v12, 16, v13
	v_pk_add_f32 v[16:17], v[16:17], 1.0 op_sel_hi:[1,0]
	v_and_b32_e32 v13, 0xffff0000, v13
	v_div_scale_f32 v26, s[0:1], v17, v17, v33
	v_rcp_f32_e32 v27, v26
	v_pk_mul_f32 v[10:11], v[10:11], v[12:13] op_sel_hi:[0,1]
	v_pk_mul_f32 v[10:11], v[4:5], v[10:11]
	v_fma_f32 v12, -v26, v27, 1.0
	v_fmac_f32_e32 v27, v12, v27
	v_div_scale_f32 v12, vcc, v33, v17, v33
	v_mul_f32_e32 v13, v12, v27
	v_fma_f32 v31, -v26, v13, v12
	v_fmac_f32_e32 v13, v31, v27
	v_fma_f32 v12, -v26, v13, v12
	v_div_scale_f32 v26, s[0:1], v16, v16, v32
	v_rcp_f32_e32 v31, v26
	v_div_fmas_f32 v12, v12, v27, v13
	v_div_fixup_f32 v13, v12, v17, v33
	v_fma_f32 v12, -v26, v31, 1.0
	v_fmac_f32_e32 v31, v12, v31
	v_div_scale_f32 v12, vcc, v32, v16, v32
	v_mul_f32_e32 v17, v12, v31
	v_fma_f32 v27, -v26, v17, v12
	v_fmac_f32_e32 v17, v27, v31
	v_fma_f32 v12, -v26, v17, v12
	v_div_fmas_f32 v12, v12, v31, v17
	v_div_fixup_f32 v12, v12, v16, v32
	v_pk_mul_f32 v[16:17], v[10:11], v[12:13]
	v_cvt_pk_bf16_f32 v10, v20, v21
	v_cvt_pk_bf16_f32 v11, v14, v15
	v_cvt_pk_bf16_f32 v12, v24, v25
	v_cvt_pk_bf16_f32 v13, v16, v17
	v_lshl_add_u64 v[14:15], s[36:37], 0, v[18:19]
	global_store_dwordx4 v[14:15], v[10:13], off sc1
	ds_read_b128 v[14:17], v29 offset:14784
	s_waitcnt lgkmcnt(0)
	v_and_b32_e32 v31, 0xffff0000, v14
	v_or_b32_e32 v10, 28, v22
	v_mov_b32_e32 v11, v23
	v_lshlrev_b64 v[26:27], 11, v[10:11]
	v_or_b32_e32 v26, v26, v28
	v_lshl_add_u64 v[10:11], s[60:61], 0, v[26:27]
	v_or_b32_e32 v22, 30, v22
	v_lshlrev_b32_e32 v34, 16, v116
	v_and_b32_e32 v18, 0xffff0000, v116
	v_mul_f32_e32 v10, 0xbfb8aa3b, v34
	v_exp_f32_e32 v32, v10
	v_mul_f32_e32 v10, 0xbfb8aa3b, v18
	v_exp_f32_e32 v33, v10
	ds_read2_b32 v[24:25], v30 offset0:156 offset1:158
	ds_read_b128 v[10:13], v29 offset:15840
	v_lshlrev_b32_e32 v30, 16, v14
	v_pk_add_f32 v[32:33], v[32:33], 1.0 op_sel_hi:[1,0]
	s_nop 0
	v_div_scale_f32 v29, s[0:1], v33, v33, v18
	v_rcp_f32_e32 v35, v29
	s_waitcnt lgkmcnt(1)
	v_pk_mul_f32 v[30:31], v[24:25], v[30:31] op_sel_hi:[0,1]
	v_pk_mul_f32 v[30:31], v[6:7], v[30:31]
	v_fma_f32 v14, -v29, v35, 1.0
	v_fmac_f32_e32 v35, v14, v35
	v_div_scale_f32 v14, vcc, v18, v33, v18
	v_mul_f32_e32 v36, v14, v35
	v_fma_f32 v37, -v29, v36, v14
	v_fmac_f32_e32 v36, v37, v35
	v_fma_f32 v14, -v29, v36, v14
	v_div_scale_f32 v29, s[0:1], v32, v32, v34
	v_rcp_f32_e32 v37, v29
	v_div_fmas_f32 v14, v14, v35, v36
	v_div_fixup_f32 v33, v14, v33, v18
	v_fma_f32 v14, -v29, v37, 1.0
	v_fmac_f32_e32 v37, v14, v37
	v_div_scale_f32 v14, vcc, v34, v32, v34
	v_mul_f32_e32 v18, v14, v37
	v_fma_f32 v35, -v29, v18, v14
	v_fmac_f32_e32 v18, v35, v37
	v_fma_f32 v14, -v29, v18, v14
	v_lshlrev_b32_e32 v29, 16, v117
	v_and_b32_e32 v35, 0xffff0000, v117
	v_div_fmas_f32 v14, v14, v37, v18
	v_mul_f32_e32 v18, 0xbfb8aa3b, v29
	v_mul_f32_e32 v19, 0xbfb8aa3b, v35
	v_exp_f32_e32 v18, v18
	v_exp_f32_e32 v19, v19
	v_div_fixup_f32 v32, v14, v32, v34
	v_pk_mul_f32 v[30:31], v[30:31], v[32:33]
	v_lshlrev_b32_e32 v14, 16, v15
	v_pk_add_f32 v[18:19], v[18:19], 1.0 op_sel_hi:[1,0]
	v_and_b32_e32 v15, 0xffff0000, v15
	v_div_scale_f32 v32, s[0:1], v19, v19, v35
	v_rcp_f32_e32 v33, v32
	v_pk_mul_f32 v[14:15], v[24:25], v[14:15] op_sel_hi:[0,1]
	v_pk_mul_f32 v[14:15], v[8:9], v[14:15]
	v_fma_f32 v34, -v32, v33, 1.0
	v_fmac_f32_e32 v33, v34, v33
	v_div_scale_f32 v34, vcc, v35, v19, v35
	v_mul_f32_e32 v36, v34, v33
	v_fma_f32 v37, -v32, v36, v34
	v_fmac_f32_e32 v36, v37, v33
	v_fma_f32 v32, -v32, v36, v34
	v_div_scale_f32 v34, s[0:1], v18, v18, v29
	v_rcp_f32_e32 v37, v34
	v_div_fmas_f32 v32, v32, v33, v36
	v_div_fixup_f32 v19, v32, v19, v35
	v_fma_f32 v32, -v34, v37, 1.0
	v_fmac_f32_e32 v37, v32, v37
	v_div_scale_f32 v32, vcc, v29, v18, v29
	v_mul_f32_e32 v33, v32, v37
	v_fma_f32 v35, -v34, v33, v32
	v_fmac_f32_e32 v33, v35, v37
	v_fma_f32 v32, -v34, v33, v32
	v_lshlrev_b32_e32 v35, 16, v118
	v_and_b32_e32 v20, 0xffff0000, v118
	v_div_fmas_f32 v34, v32, v37, v33
	v_mul_f32_e32 v32, 0xbfb8aa3b, v35
	v_mul_f32_e32 v33, 0xbfb8aa3b, v20
	v_exp_f32_e32 v32, v32
	v_exp_f32_e32 v33, v33
	v_div_fixup_f32 v18, v34, v18, v29
	v_pk_mul_f32 v[18:19], v[14:15], v[18:19]
	v_lshlrev_b32_e32 v14, 16, v16
	v_pk_add_f32 v[32:33], v[32:33], 1.0 op_sel_hi:[1,0]
	v_and_b32_e32 v15, 0xffff0000, v16
	v_div_scale_f32 v29, s[0:1], v33, v33, v20
	v_rcp_f32_e32 v34, v29
	v_pk_mul_f32 v[14:15], v[24:25], v[14:15] op_sel_hi:[0,1]
	v_pk_mul_f32 v[14:15], v[2:3], v[14:15]
	v_fma_f32 v16, -v29, v34, 1.0
	v_fmac_f32_e32 v34, v16, v34
	v_div_scale_f32 v16, vcc, v20, v33, v20
	v_mul_f32_e32 v36, v16, v34
	v_fma_f32 v37, -v29, v36, v16
	v_fmac_f32_e32 v36, v37, v34
	v_fma_f32 v16, -v29, v36, v16
	v_div_scale_f32 v29, s[0:1], v32, v32, v35
	v_rcp_f32_e32 v37, v29
	v_div_fmas_f32 v16, v16, v34, v36
	v_div_fixup_f32 v33, v16, v33, v20
	v_fma_f32 v16, -v29, v37, 1.0
	v_fmac_f32_e32 v37, v16, v37
	v_div_scale_f32 v16, vcc, v35, v32, v35
	v_mul_f32_e32 v20, v16, v37
	v_fma_f32 v34, -v29, v20, v16
	v_fmac_f32_e32 v20, v34, v37
	v_fma_f32 v16, -v29, v20, v16
	v_lshlrev_b32_e32 v29, 16, v119
	v_and_b32_e32 v34, 0xffff0000, v119
	v_div_fmas_f32 v16, v16, v37, v20
	v_mul_f32_e32 v20, 0xbfb8aa3b, v29
	v_mul_f32_e32 v21, 0xbfb8aa3b, v34
	v_exp_f32_e32 v20, v20
	v_exp_f32_e32 v21, v21
	v_div_fixup_f32 v32, v16, v32, v35
	v_pk_mul_f32 v[32:33], v[14:15], v[32:33]
	v_lshlrev_b32_e32 v14, 16, v17
	v_pk_add_f32 v[20:21], v[20:21], 1.0 op_sel_hi:[1,0]
	v_and_b32_e32 v15, 0xffff0000, v17
	v_div_scale_f32 v16, s[0:1], v21, v21, v34
	v_rcp_f32_e32 v35, v16
	v_pk_mul_f32 v[14:15], v[24:25], v[14:15] op_sel_hi:[0,1]
	v_pk_mul_f32 v[14:15], v[4:5], v[14:15]
	v_fma_f32 v17, -v16, v35, 1.0
	v_fmac_f32_e32 v35, v17, v35
	v_div_scale_f32 v17, vcc, v34, v21, v34
	v_mul_f32_e32 v24, v17, v35
	v_fma_f32 v36, -v16, v24, v17
	v_fmac_f32_e32 v24, v36, v35
	v_div_scale_f32 v36, s[0:1], v20, v20, v29
	v_rcp_f32_e32 v37, v36
	v_fma_f32 v16, -v16, v24, v17
	v_div_fmas_f32 v16, v16, v35, v24
	v_div_fixup_f32 v17, v16, v21, v34
	v_fma_f32 v16, -v36, v37, 1.0
	v_fmac_f32_e32 v37, v16, v37
	v_div_scale_f32 v16, vcc, v29, v20, v29
	v_mul_f32_e32 v21, v16, v37
	v_fma_f32 v24, -v36, v21, v16
	v_fmac_f32_e32 v21, v24, v37
	v_fma_f32 v16, -v36, v21, v16
	v_div_fmas_f32 v16, v16, v37, v21
	v_div_fixup_f32 v16, v16, v20, v29
	v_pk_mul_f32 v[20:21], v[14:15], v[16:17]
	v_cvt_pk_bf16_f32 v14, v30, v31
	v_cvt_pk_bf16_f32 v15, v18, v19
	v_cvt_pk_bf16_f32 v16, v32, v33
	v_cvt_pk_bf16_f32 v17, v20, v21
	v_lshl_add_u64 v[18:19], s[36:37], 0, v[26:27]
	global_store_dwordx4 v[18:19], v[14:17], off sc1
	v_lshlrev_b64 v[18:19], 11, v[22:23]
	v_or_b32_e32 v18, v18, v28
	v_lshl_add_u64 v[14:15], s[60:61], 0, v[18:19]
	s_waitcnt lgkmcnt(0)
	v_lshlrev_b32_e32 v22, 16, v10
	v_and_b32_e32 v23, 0xffff0000, v10
	v_mov_b32_e32 v10, v25
	v_pk_mul_f32 v[22:23], v[10:11], v[22:23] op_sel_hi:[0,1]
	v_pk_mul_f32 v[6:7], v[6:7], v[22:23]
	v_lshlrev_b32_e32 v24, 16, v120
	v_and_b32_e32 v14, 0xffff0000, v120
	v_mul_f32_e32 v20, 0xbfb8aa3b, v24
	v_mul_f32_e32 v21, 0xbfb8aa3b, v14
	v_exp_f32_e32 v20, v20
	v_exp_f32_e32 v21, v21
	s_nop 0
	v_pk_add_f32 v[20:21], v[20:21], 1.0 op_sel_hi:[1,0]
	s_nop 0
	v_div_scale_f32 v26, s[0:1], v21, v21, v14
	v_rcp_f32_e32 v27, v26
	s_nop 0
	v_fma_f32 v22, -v26, v27, 1.0
	v_fmac_f32_e32 v27, v22, v27
	v_div_scale_f32 v22, vcc, v14, v21, v14
	v_mul_f32_e32 v23, v22, v27
	v_fma_f32 v25, -v26, v23, v22
	v_fmac_f32_e32 v23, v25, v27
	v_div_scale_f32 v25, s[0:1], v20, v20, v24
	v_fma_f32 v22, -v26, v23, v22
	v_rcp_f32_e32 v26, v25
	v_div_fmas_f32 v22, v22, v27, v23
	v_div_fixup_f32 v21, v22, v21, v14
	v_fma_f32 v14, -v25, v26, 1.0
	v_fmac_f32_e32 v26, v14, v26
	v_div_scale_f32 v14, vcc, v24, v20, v24
	v_mul_f32_e32 v22, v14, v26
	v_fma_f32 v23, -v25, v22, v14
	v_fmac_f32_e32 v22, v23, v26
	v_fma_f32 v14, -v25, v22, v14
	v_lshlrev_b32_e32 v23, 16, v121
	v_and_b32_e32 v25, 0xffff0000, v121
	v_div_fmas_f32 v22, v14, v26, v22
	v_mul_f32_e32 v14, 0xbfb8aa3b, v23
	v_mul_f32_e32 v15, 0xbfb8aa3b, v25
	v_exp_f32_e32 v14, v14
	v_exp_f32_e32 v15, v15
	v_div_fixup_f32 v20, v22, v20, v24
	v_pk_mul_f32 v[6:7], v[6:7], v[20:21]
	v_lshlrev_b32_e32 v20, 16, v11
	v_pk_add_f32 v[14:15], v[14:15], 1.0 op_sel_hi:[1,0]
	v_and_b32_e32 v21, 0xffff0000, v11
	v_div_scale_f32 v22, s[0:1], v15, v15, v25
	v_rcp_f32_e32 v24, v22
	v_pk_mul_f32 v[20:21], v[10:11], v[20:21] op_sel_hi:[0,1]
	v_pk_mul_f32 v[8:9], v[8:9], v[20:21]
	v_fma_f32 v11, -v22, v24, 1.0
	v_fmac_f32_e32 v24, v11, v24
	v_div_scale_f32 v11, vcc, v25, v15, v25
	v_mul_f32_e32 v20, v11, v24
	v_fma_f32 v21, -v22, v20, v11
	v_fmac_f32_e32 v20, v21, v24
	v_div_scale_f32 v21, s[0:1], v14, v14, v23
	v_fma_f32 v11, -v22, v20, v11
	v_rcp_f32_e32 v22, v21
	v_div_fmas_f32 v11, v11, v24, v20
	v_div_fixup_f32 v15, v11, v15, v25
	v_fma_f32 v11, -v21, v22, 1.0
	v_fmac_f32_e32 v22, v11, v22
	v_div_scale_f32 v11, vcc, v23, v14, v23
	v_mul_f32_e32 v20, v11, v22
	v_fma_f32 v24, -v21, v20, v11
	v_fmac_f32_e32 v20, v24, v22
	v_fma_f32 v11, -v21, v20, v11
	v_div_fmas_f32 v11, v11, v22, v20
	v_lshlrev_b32_e32 v22, 16, v122
	v_and_b32_e32 v16, 0xffff0000, v122
	v_mul_f32_e32 v20, 0xbfb8aa3b, v22
	v_mul_f32_e32 v21, 0xbfb8aa3b, v16
	v_exp_f32_e32 v20, v20
	v_exp_f32_e32 v21, v21
	v_div_fixup_f32 v14, v11, v14, v23
	v_pk_mul_f32 v[8:9], v[8:9], v[14:15]
	v_lshlrev_b32_e32 v14, 16, v12
	v_pk_add_f32 v[20:21], v[20:21], 1.0 op_sel_hi:[1,0]
	v_and_b32_e32 v15, 0xffff0000, v12
	v_div_scale_f32 v11, s[0:1], v21, v21, v16
	v_rcp_f32_e32 v23, v11
	v_pk_mul_f32 v[14:15], v[10:11], v[14:15] op_sel_hi:[0,1]
	v_pk_mul_f32 v[2:3], v[2:3], v[14:15]
	v_fma_f32 v12, -v11, v23, 1.0
	v_fmac_f32_e32 v23, v12, v23
	v_div_scale_f32 v12, vcc, v16, v21, v16
	v_mul_f32_e32 v14, v12, v23
	v_fma_f32 v15, -v11, v14, v12
	v_fmac_f32_e32 v14, v15, v23
	v_fma_f32 v11, -v11, v14, v12
	v_div_scale_f32 v12, s[0:1], v20, v20, v22
	v_rcp_f32_e32 v24, v12
	v_div_fmas_f32 v11, v11, v23, v14
	v_div_fixup_f32 v15, v11, v21, v16
	v_and_b32_e32 v21, 0xffff0000, v123
	v_fma_f32 v11, -v12, v24, 1.0
	v_fmac_f32_e32 v24, v11, v24
	v_div_scale_f32 v11, vcc, v22, v20, v22
	v_mul_f32_e32 v14, v11, v24
	v_fma_f32 v16, -v12, v14, v11
	v_fmac_f32_e32 v14, v16, v24
	v_fma_f32 v11, -v12, v14, v11
	v_lshlrev_b32_e32 v12, 16, v123
	v_div_fmas_f32 v11, v11, v24, v14
	v_mul_f32_e32 v14, 0xbfb8aa3b, v12
	v_exp_f32_e32 v16, v14
	v_mul_f32_e32 v14, 0xbfb8aa3b, v21
	v_exp_f32_e32 v17, v14
	v_div_fixup_f32 v14, v11, v20, v22
	v_pk_mul_f32 v[14:15], v[2:3], v[14:15]
	v_lshlrev_b32_e32 v2, 16, v13
	v_pk_add_f32 v[16:17], v[16:17], 1.0 op_sel_hi:[1,0]
	v_and_b32_e32 v3, 0xffff0000, v13
	v_div_scale_f32 v11, s[0:1], v17, v17, v21
	v_rcp_f32_e32 v20, v11
	v_pk_mul_f32 v[2:3], v[10:11], v[2:3] op_sel_hi:[0,1]
	v_pk_mul_f32 v[2:3], v[4:5], v[2:3]
	v_fma_f32 v4, -v11, v20, 1.0
	v_fmac_f32_e32 v20, v4, v20
	v_div_scale_f32 v4, vcc, v21, v17, v21
	v_mul_f32_e32 v5, v4, v20
	v_fma_f32 v10, -v11, v5, v4
	v_fmac_f32_e32 v5, v10, v20
	v_div_scale_f32 v10, s[0:1], v16, v16, v12
	v_fma_f32 v4, -v11, v5, v4
	v_rcp_f32_e32 v11, v10
	v_div_fmas_f32 v4, v4, v20, v5
	v_div_fixup_f32 v5, v4, v17, v21
	v_fma_f32 v4, -v10, v11, 1.0
	v_fmac_f32_e32 v11, v4, v11
	v_div_scale_f32 v4, vcc, v12, v16, v12
	v_mul_f32_e32 v13, v4, v11
	v_fma_f32 v17, -v10, v13, v4
	v_fmac_f32_e32 v13, v17, v11
	v_fma_f32 v4, -v10, v13, v4
	v_div_fmas_f32 v4, v4, v11, v13
	v_div_fixup_f32 v4, v4, v16, v12
	v_pk_mul_f32 v[10:11], v[2:3], v[4:5]
	v_cvt_pk_bf16_f32 v2, v6, v7
	v_cvt_pk_bf16_f32 v3, v8, v9
	v_cvt_pk_bf16_f32 v4, v14, v15
	v_cvt_pk_bf16_f32 v5, v10, v11
	v_lshl_add_u64 v[6:7], s[36:37], 0, v[18:19]
	global_store_dwordx4 v[6:7], v[2:5], off sc1
	s_waitcnt vmcnt(0)
	s_barrier
	s_and_saveexec_b64 s[0:1], s[14:15]
	s_cbranch_execz .LBB0_1429
	s_add_i32 s6, 0, 0x22160
	v_mov_b32_e32 v2, s6
	s_waitcnt vmcnt(0) expcnt(0) lgkmcnt(0)
	ds_read_b32 v4, v2
	s_add_i32 s6, 0, 0x22164
	v_mov_b32_e32 v2, s6
	ds_read_b32 v2, v2
	s_waitcnt lgkmcnt(1)
	v_cmp_ne_u32_e32 vcc, 0, v4
	s_cbranch_vccnz .LBB0_1393
	v_readlane_b32 s8, v251, 53
	v_readlane_b32 s9, v251, 54
	s_load_dwordx2 s[6:7], s[8:9], 0x4
	s_mov_b32 s33, 1
	v_mov_b32_e32 v18, 0
	s_waitcnt lgkmcnt(0)
	s_mul_i32 s6, s6, s7
	s_lshl_b32 s60, s6, 8
	s_add_u32 s6, s34, 0x4200
	s_addc_u32 s7, s35, 0
	s_add_u32 s8, s34, 0x4400
	s_addc_u32 s9, s35, 0
	s_add_u32 s10, s34, 0x4500
	s_addc_u32 s11, s35, 0
	s_add_u32 s12, s34, 0x4600
	s_addc_u32 s13, s35, 0
	s_add_u32 s16, s34, 0x4700
	s_addc_u32 s17, s35, 0
	s_add_u32 s18, s34, 0x4800
	s_addc_u32 s19, s35, 0
	s_add_u32 s20, s34, 0x4900
	s_addc_u32 s21, s35, 0
	s_add_u32 s22, s34, 0x4a00
	s_addc_u32 s23, s35, 0
	s_add_u32 s24, s34, 0x4b00
	s_addc_u32 s25, s35, 0
	s_add_u32 s26, s34, 0x4c00
	s_addc_u32 s27, s35, 0
	s_add_u32 s28, s34, 0x4d00
	s_addc_u32 s29, s35, 0
	s_add_u32 s30, s34, 0x4e00
	s_addc_u32 s31, s35, 0
	s_add_u32 s38, s34, 0x4f00
	s_addc_u32 s39, s35, 0
	s_add_u32 s40, s34, 0x5000
	s_addc_u32 s41, s35, 0
	s_add_u32 s42, s34, 0x5100
	s_addc_u32 s43, s35, 0
	s_add_u32 s44, s34, 0x5200
	s_addc_u32 s45, s35, 0
	s_add_u32 s46, s34, 0x5300
	s_addc_u32 s47, s35, 0
	s_branch .LBB0_1381
